# best kernel plus 4 wait states after each 16-byte epilogue store in the re-ordered GEMM epilogues (hazard safety margin)
# speedup vs baseline: 1.0015x; 1.0015x over previous
; #define GAS __attribute__((address_space(1)))
; __device__ __forceinline__ unsigned cvt_pk_bf16(float lo, float hi) { unsigned r; asm volatile("v_cvt_pk_bf16_f32 %0, %1, %2" : "=v"(r) : "v"(lo), "v"(hi)); return r; }
; __device__ __forceinline__ float bf_lo(unsigned w) { return __uint_as_float(w << 16); }
; __device__ __forceinline__ float bf_hi(unsigned w) { return __uint_as_float(w & 0xffff0000u); }
;     __device__ __forceinline__ void operator()(const f32x4 (&acc)[2][2][4][2], const Unit& u, int wr, int wc, int fr, int fq) const {
;     ...
;             for (int m = 0; m < 4; ++m) { const size_t off = (size_t)(row0 + ai * HALF + m * 16) * DM + col0; q[ai][m] = 0.f;
; #pragma unroll
;                 for (int bj = 0; bj < 2; ++bj) { f32x4 b0, b1;
;                     if (baseb) { const u32x4 bw = *(const GAS u32x4*)(baseb + off + bj * HALF); b0 = (f32x4){bf_lo(bw.x), bf_hi(bw.x), bf_lo(bw.y), bf_hi(bw.y)}; b1 = (f32x4){bf_lo(bw.z), bf_hi(bw.z), bf_lo(bw.w), bf_hi(bw.w)}; }
;                     else { b0 = *(const GAS f32x4*)(base + off + bj * HALF); b1 = *(const GAS f32x4*)(base + off + bj * HALF + 4); }
;                     const f32x4 o0 = b0 + acc[ai][bj][m][0], o1 = b1 + acc[ai][bj][m][1];
;                     if (out) { *(GAS f32x4*)(out + off + bj * HALF) = o0; *(GAS f32x4*)(out + off + bj * HALF + 4) = o1; }
;                     q[ai][m] += (o0[0] * o0[0] + o0[1] * o0[1]) + (o0[2] * o0[2] + o0[3] * o0[3]) + (o1[0] * o1[0] + o1[1] * o1[1]) + (o1[2] * o1[2] + o1[3] * o1[3]);
;                     if (xb) { u32x4 w; w.x = cvt_pk_bf16(o0[0], o0[1]); w.y = cvt_pk_bf16(o0[2], o0[3]); w.z = cvt_pk_bf16(o1[0], o1[1]); w.w = cvt_pk_bf16(o1[2], o1[3]); *(GAS u32x4*)(xb + off + bj * HALF) = w; } } }
.LBB0_141:
	v_lshl_add_u32 v142, s52, 8, v144
	v_lshl_or_b32 v140, s51, 8, v146
	v_ashrrev_i32_e32 v143, 31, v142
	v_ashrrev_i32_e32 v141, 31, v140
	v_lshlrev_b64 v[138:139], 11, v[142:143]
	v_lshl_add_u64 v[138:139], v[138:139], 0, v[140:141]
	v_lshlrev_b64 v[138:139], 1, v[138:139]
	v_add_u32_e32 v159, 0x10000, v138
	v_add_u32_e32 v160, 0x20000, v138
	v_add_u32_e32 v161, 0x30000, v138
	global_load_dwordx4 v[164:167], v138, s[6:7]
	global_load_dwordx4 v[168:171], v138, s[6:7] offset:256
	global_load_dwordx4 v[172:175], v159, s[6:7]
	global_load_dwordx4 v[176:179], v159, s[6:7] offset:256
	global_load_dwordx4 v[180:183], v160, s[6:7]
	global_load_dwordx4 v[188:191], v160, s[6:7] offset:256
	global_load_dwordx4 v[192:195], v161, s[6:7]
	global_load_dwordx4 v[196:199], v161, s[6:7] offset:256
	v_lshl_add_u64 v[152:153], s[6:7], 0, v[138:139]
	s_mov_b64 s[38:39], 0x80000
	s_and_b64 vcc, exec, s[36:37]
	s_mov_b64 s[36:37], -1
	s_waitcnt vmcnt(0)
	v_mov_b32_e32 v148, v164
	v_mov_b32_e32 v149, v165
	v_mov_b32_e32 v150, v166
	v_mov_b32_e32 v151, v167
	v_lshlrev_b32_e32 v154, 16, v148
	v_and_b32_e32 v155, 0xffff0000, v148
	v_lshlrev_b32_e32 v148, 16, v149
	v_and_b32_e32 v149, 0xffff0000, v149
	v_lshlrev_b32_e32 v156, 16, v150
	v_and_b32_e32 v157, 0xffff0000, v150
	v_lshlrev_b32_e32 v150, 16, v151
	v_and_b32_e32 v151, 0xffff0000, v151
	v_pk_add_f32 v[126:127], v[126:127], v[148:149]
	v_pk_add_f32 v[124:125], v[124:125], v[154:155]
	v_pk_add_f32 v[148:149], v[122:123], v[150:151]
	v_pk_add_f32 v[122:123], v[120:121], v[156:157]
	v_cvt_pk_bf16_f32 v120, v124, v125
	v_cvt_pk_bf16_f32 v121, v126, v127
	v_lshl_add_u64 v[150:151], s[34:35], 0, v[138:139]
	v_cvt_pk_bf16_f32 v122, v122, v123
	v_cvt_pk_bf16_f32 v123, v148, v149
	v_mov_b32_e32 v124, v168
	v_mov_b32_e32 v125, v169
	v_mov_b32_e32 v126, v170
	v_mov_b32_e32 v127, v171
	v_or_b32_e32 v148, 16, v142
	v_ashrrev_i32_e32 v149, 31, v148
	v_lshlrev_b64 v[148:149], 11, v[148:149]
	v_lshl_add_u64 v[148:149], v[148:149], 0, v[140:141]
	global_store_dwordx4 v[150:151], v[120:123], off
	s_nop 3
	v_lshlrev_b64 v[148:149], 1, v[148:149]
	v_lshl_add_u64 v[152:153], s[6:7], 0, v[148:149]
	v_lshlrev_b32_e32 v120, 16, v124
	v_and_b32_e32 v121, 0xffff0000, v124
	v_lshlrev_b32_e32 v122, 16, v125
	v_and_b32_e32 v123, 0xffff0000, v125
	v_lshlrev_b32_e32 v124, 16, v126
	v_and_b32_e32 v125, 0xffff0000, v126
	v_lshlrev_b32_e32 v126, 16, v127
	v_and_b32_e32 v127, 0xffff0000, v127
	v_pk_add_f32 v[116:117], v[116:117], v[120:121]
	v_pk_add_f32 v[120:121], v[114:115], v[126:127]
	v_pk_add_f32 v[114:115], v[112:113], v[124:125]
	v_pk_add_f32 v[118:119], v[118:119], v[122:123]
	v_cvt_pk_bf16_f32 v112, v116, v117
	s_nop 0
	v_cvt_pk_bf16_f32 v113, v118, v119
	v_cvt_pk_bf16_f32 v114, v114, v115
	v_cvt_pk_bf16_f32 v115, v120, v121
	global_store_dwordx4 v[150:151], v[112:115], off offset:256
	s_nop 3
	s_nop 1
	v_mov_b32_e32 v112, v172
	v_mov_b32_e32 v113, v173
	v_mov_b32_e32 v114, v174
	v_mov_b32_e32 v115, v175
	v_lshlrev_b32_e32 v116, 16, v112
	v_and_b32_e32 v117, 0xffff0000, v112
	v_lshlrev_b32_e32 v112, 16, v113
	v_and_b32_e32 v113, 0xffff0000, v113
	v_lshlrev_b32_e32 v118, 16, v114
	v_and_b32_e32 v119, 0xffff0000, v114
	v_lshlrev_b32_e32 v114, 16, v115
	v_and_b32_e32 v115, 0xffff0000, v115
	v_pk_add_f32 v[110:111], v[110:111], v[112:113]
	v_pk_add_f32 v[108:109], v[108:109], v[116:117]
	v_pk_add_f32 v[112:113], v[106:107], v[114:115]
	v_pk_add_f32 v[106:107], v[104:105], v[118:119]
	v_cvt_pk_bf16_f32 v104, v108, v109
	v_cvt_pk_bf16_f32 v105, v110, v111
	v_lshl_add_u64 v[114:115], s[34:35], 0, v[148:149]
	v_cvt_pk_bf16_f32 v106, v106, v107
	v_cvt_pk_bf16_f32 v107, v112, v113
	v_mov_b32_e32 v108, v176
	v_mov_b32_e32 v109, v177
	v_mov_b32_e32 v110, v178
	v_mov_b32_e32 v111, v179
	v_or_b32_e32 v112, 32, v142
	v_ashrrev_i32_e32 v113, 31, v112
	v_lshlrev_b64 v[112:113], 11, v[112:113]
	v_lshl_add_u64 v[112:113], v[112:113], 0, v[140:141]
	global_store_dwordx4 v[114:115], v[104:107], off
	s_nop 3
	v_lshlrev_b64 v[112:113], 1, v[112:113]
	v_lshl_add_u64 v[116:117], s[6:7], 0, v[112:113]
	v_lshlrev_b32_e32 v104, 16, v108
	v_and_b32_e32 v105, 0xffff0000, v108
	v_lshlrev_b32_e32 v106, 16, v109
	v_and_b32_e32 v107, 0xffff0000, v109
	v_lshlrev_b32_e32 v108, 16, v110
	v_and_b32_e32 v109, 0xffff0000, v110
	v_lshlrev_b32_e32 v110, 16, v111
	v_and_b32_e32 v111, 0xffff0000, v111
	v_pk_add_f32 v[100:101], v[100:101], v[104:105]
	v_pk_add_f32 v[104:105], v[98:99], v[110:111]
	v_pk_add_f32 v[98:99], v[96:97], v[108:109]
	v_pk_add_f32 v[102:103], v[102:103], v[106:107]
	v_cvt_pk_bf16_f32 v96, v100, v101
	s_nop 0
	v_cvt_pk_bf16_f32 v97, v102, v103
	v_cvt_pk_bf16_f32 v98, v98, v99
	v_cvt_pk_bf16_f32 v99, v104, v105
	global_store_dwordx4 v[114:115], v[96:99], off offset:256
	s_nop 3
	s_nop 1
	v_mov_b32_e32 v96, v180
	v_mov_b32_e32 v97, v181
	v_mov_b32_e32 v98, v182
	v_mov_b32_e32 v99, v183
	v_lshlrev_b32_e32 v100, 16, v96
	v_and_b32_e32 v101, 0xffff0000, v96
	v_lshlrev_b32_e32 v96, 16, v97
	v_and_b32_e32 v97, 0xffff0000, v97
	v_lshlrev_b32_e32 v102, 16, v98
	v_and_b32_e32 v103, 0xffff0000, v98
	v_lshlrev_b32_e32 v98, 16, v99
	v_and_b32_e32 v99, 0xffff0000, v99
	v_pk_add_f32 v[94:95], v[94:95], v[96:97]
	v_pk_add_f32 v[92:93], v[92:93], v[100:101]
	v_pk_add_f32 v[96:97], v[90:91], v[98:99]
	v_pk_add_f32 v[90:91], v[88:89], v[102:103]
	v_cvt_pk_bf16_f32 v88, v92, v93
	v_cvt_pk_bf16_f32 v89, v94, v95
	v_lshl_add_u64 v[98:99], s[34:35], 0, v[112:113]
	v_cvt_pk_bf16_f32 v90, v90, v91
	v_cvt_pk_bf16_f32 v91, v96, v97
	v_mov_b32_e32 v92, v188
	v_mov_b32_e32 v93, v189
	v_mov_b32_e32 v94, v190
	v_mov_b32_e32 v95, v191
	v_or_b32_e32 v96, 48, v142
; #define GAS __attribute__((address_space(1)))
; __device__ __forceinline__ unsigned cvt_pk_bf16(float lo, float hi) { unsigned r; asm volatile("v_cvt_pk_bf16_f32 %0, %1, %2" : "=v"(r) : "v"(lo), "v"(hi)); return r; }
; __device__ __forceinline__ float bf_lo(unsigned w) { return __uint_as_float(w << 16); }
; __device__ __forceinline__ float bf_hi(unsigned w) { return __uint_as_float(w & 0xffff0000u); }
;     __device__ __forceinline__ void operator()(const f32x4 (&acc)[2][2][4][2], const Unit& u, int wr, int wc, int fr, int fq) const {
;     ...
;             for (int m = 0; m < 4; ++m) { const size_t off = (size_t)(row0 + ai * HALF + m * 16) * DM + col0; q[ai][m] = 0.f;
; #pragma unroll
;                 for (int bj = 0; bj < 2; ++bj) { f32x4 b0, b1;
;                     if (baseb) { const u32x4 bw = *(const GAS u32x4*)(baseb + off + bj * HALF); b0 = (f32x4){bf_lo(bw.x), bf_hi(bw.x), bf_lo(bw.y), bf_hi(bw.y)}; b1 = (f32x4){bf_lo(bw.z), bf_hi(bw.z), bf_lo(bw.w), bf_hi(bw.w)}; }
;                     else { b0 = *(const GAS f32x4*)(base + off + bj * HALF); b1 = *(const GAS f32x4*)(base + off + bj * HALF + 4); }
;                     const f32x4 o0 = b0 + acc[ai][bj][m][0], o1 = b1 + acc[ai][bj][m][1];
;                     if (out) { *(GAS f32x4*)(out + off + bj * HALF) = o0; *(GAS f32x4*)(out + off + bj * HALF + 4) = o1; }
;                     q[ai][m] += (o0[0] * o0[0] + o0[1] * o0[1]) + (o0[2] * o0[2] + o0[3] * o0[3]) + (o1[0] * o1[0] + o1[1] * o1[1]) + (o1[2] * o1[2] + o1[3] * o1[3]);
;                     if (xb) { u32x4 w; w.x = cvt_pk_bf16(o0[0], o0[1]); w.y = cvt_pk_bf16(o0[2], o0[3]); w.z = cvt_pk_bf16(o1[0], o1[1]); w.w = cvt_pk_bf16(o1[2], o1[3]); *(GAS u32x4*)(xb + off + bj * HALF) = w; } } }
	v_ashrrev_i32_e32 v97, 31, v96
	v_lshlrev_b64 v[96:97], 11, v[96:97]
	v_lshl_add_u64 v[96:97], v[96:97], 0, v[140:141]
	global_store_dwordx4 v[98:99], v[88:91], off
	s_nop 3
	v_lshlrev_b64 v[96:97], 1, v[96:97]
	v_lshl_add_u64 v[100:101], s[6:7], 0, v[96:97]
	v_lshlrev_b32_e32 v88, 16, v92
	v_and_b32_e32 v89, 0xffff0000, v92
	v_lshlrev_b32_e32 v90, 16, v93
	v_and_b32_e32 v91, 0xffff0000, v93
	v_lshlrev_b32_e32 v92, 16, v94
	v_and_b32_e32 v93, 0xffff0000, v94
	v_lshlrev_b32_e32 v94, 16, v95
	v_and_b32_e32 v95, 0xffff0000, v95
	v_pk_add_f32 v[84:85], v[84:85], v[88:89]
	v_pk_add_f32 v[88:89], v[82:83], v[94:95]
	v_pk_add_f32 v[82:83], v[80:81], v[92:93]
	v_pk_add_f32 v[86:87], v[86:87], v[90:91]
	v_cvt_pk_bf16_f32 v80, v84, v85
	s_nop 0
	v_cvt_pk_bf16_f32 v81, v86, v87
	v_cvt_pk_bf16_f32 v82, v82, v83
	v_cvt_pk_bf16_f32 v83, v88, v89
	global_store_dwordx4 v[98:99], v[80:83], off offset:256
	s_nop 3
	s_nop 1
	v_mov_b32_e32 v80, v192
	v_mov_b32_e32 v81, v193
	v_mov_b32_e32 v82, v194
	v_mov_b32_e32 v83, v195
	v_lshlrev_b32_e32 v84, 16, v80
	v_and_b32_e32 v85, 0xffff0000, v80
	v_lshlrev_b32_e32 v80, 16, v81
	v_and_b32_e32 v81, 0xffff0000, v81
	v_lshlrev_b32_e32 v86, 16, v82
	v_and_b32_e32 v87, 0xffff0000, v82
	v_lshlrev_b32_e32 v82, 16, v83
	v_and_b32_e32 v83, 0xffff0000, v83
	v_pk_add_f32 v[78:79], v[78:79], v[80:81]
	v_pk_add_f32 v[76:77], v[76:77], v[84:85]
	v_pk_add_f32 v[80:81], v[74:75], v[82:83]
	v_pk_add_f32 v[74:75], v[72:73], v[86:87]
	v_cvt_pk_bf16_f32 v72, v76, v77
	v_cvt_pk_bf16_f32 v73, v78, v79
	v_lshl_add_u64 v[82:83], s[34:35], 0, v[96:97]
	v_cvt_pk_bf16_f32 v74, v74, v75
	v_cvt_pk_bf16_f32 v75, v80, v81
	v_mov_b32_e32 v76, v196
	v_mov_b32_e32 v77, v197
	v_mov_b32_e32 v78, v198
	v_mov_b32_e32 v79, v199
	v_lshl_add_u64 v[80:81], v[138:139], 0, s[38:39]
	global_store_dwordx4 v[82:83], v[72:75], off
	s_nop 3
	v_lshl_add_u64 v[84:85], s[6:7], 0, v[80:81]
	s_mov_b64 s[38:39], 0xa0000
	v_lshlrev_b32_e32 v72, 16, v76
	v_and_b32_e32 v73, 0xffff0000, v76
	v_lshlrev_b32_e32 v74, 16, v77
	v_and_b32_e32 v75, 0xffff0000, v77
	v_lshlrev_b32_e32 v76, 16, v78
	v_and_b32_e32 v77, 0xffff0000, v78
	v_lshlrev_b32_e32 v78, 16, v79
	v_and_b32_e32 v79, 0xffff0000, v79
	v_pk_add_f32 v[68:69], v[68:69], v[72:73]
	v_pk_add_f32 v[72:73], v[66:67], v[78:79]
	v_pk_add_f32 v[66:67], v[64:65], v[76:77]
	v_pk_add_f32 v[70:71], v[70:71], v[74:75]
	v_cvt_pk_bf16_f32 v64, v68, v69
	s_nop 0
	v_cvt_pk_bf16_f32 v65, v70, v71
	v_cvt_pk_bf16_f32 v66, v66, v67
	v_cvt_pk_bf16_f32 v67, v72, v73
	global_store_dwordx4 v[82:83], v[64:67], off offset:256
	s_nop 3
	v_add_u32_e32 v159, 0x80000, v138
	v_add_u32_e32 v160, 0x90000, v138
	v_add_u32_e32 v161, 0xa0000, v138
	v_add_u32_e32 v162, 0xb0000, v138
	global_load_dwordx4 v[164:167], v159, s[6:7]
	global_load_dwordx4 v[168:171], v159, s[6:7] offset:256
	global_load_dwordx4 v[172:175], v160, s[6:7]
	global_load_dwordx4 v[176:179], v160, s[6:7] offset:256
	global_load_dwordx4 v[180:183], v161, s[6:7]
	global_load_dwordx4 v[188:191], v161, s[6:7] offset:256
	global_load_dwordx4 v[192:195], v162, s[6:7]
	global_load_dwordx4 v[196:199], v162, s[6:7] offset:256
	s_waitcnt vmcnt(0)
; #define GAS __attribute__((address_space(1)))
; __device__ __forceinline__ unsigned cvt_pk_bf16(float lo, float hi) { unsigned r; asm volatile("v_cvt_pk_bf16_f32 %0, %1, %2" : "=v"(r) : "v"(lo), "v"(hi)); return r; }
; __device__ __forceinline__ float bf_lo(unsigned w) { return __uint_as_float(w << 16); }
; __device__ __forceinline__ float bf_hi(unsigned w) { return __uint_as_float(w & 0xffff0000u); }
;     __device__ __forceinline__ void operator()(const f32x4 (&acc)[2][2][4][2], const Unit& u, int wr, int wc, int fr, int fq) const {
;     ...
;             for (int m = 0; m < 4; ++m) { const size_t off = (size_t)(row0 + ai * HALF + m * 16) * DM + col0; q[ai][m] = 0.f;
; #pragma unroll
;                 for (int bj = 0; bj < 2; ++bj) { f32x4 b0, b1;
;                     if (baseb) { const u32x4 bw = *(const GAS u32x4*)(baseb + off + bj * HALF); b0 = (f32x4){bf_lo(bw.x), bf_hi(bw.x), bf_lo(bw.y), bf_hi(bw.y)}; b1 = (f32x4){bf_lo(bw.z), bf_hi(bw.z), bf_lo(bw.w), bf_hi(bw.w)}; }
;                     else { b0 = *(const GAS f32x4*)(base + off + bj * HALF); b1 = *(const GAS f32x4*)(base + off + bj * HALF + 4); }
;                     const f32x4 o0 = b0 + acc[ai][bj][m][0], o1 = b1 + acc[ai][bj][m][1];
;                     if (out) { *(GAS f32x4*)(out + off + bj * HALF) = o0; *(GAS f32x4*)(out + off + bj * HALF + 4) = o1; }
;                     q[ai][m] += (o0[0] * o0[0] + o0[1] * o0[1]) + (o0[2] * o0[2] + o0[3] * o0[3]) + (o1[0] * o1[0] + o1[1] * o1[1]) + (o1[2] * o1[2] + o1[3] * o1[3]);
;                     if (xb) { u32x4 w; w.x = cvt_pk_bf16(o0[0], o0[1]); w.y = cvt_pk_bf16(o0[2], o0[3]); w.z = cvt_pk_bf16(o1[0], o1[1]); w.w = cvt_pk_bf16(o1[2], o1[3]); *(GAS u32x4*)(xb + off + bj * HALF) = w; } } }
	v_mov_b32_e32 v64, v164
	v_mov_b32_e32 v65, v165
	v_mov_b32_e32 v66, v166
	v_mov_b32_e32 v67, v167
	v_lshlrev_b32_e32 v68, 16, v64
	v_and_b32_e32 v69, 0xffff0000, v64
	v_lshlrev_b32_e32 v64, 16, v65
	v_and_b32_e32 v65, 0xffff0000, v65
	v_lshlrev_b32_e32 v70, 16, v66
	v_and_b32_e32 v71, 0xffff0000, v66
	v_lshlrev_b32_e32 v66, 16, v67
	v_and_b32_e32 v67, 0xffff0000, v67
	v_pk_add_f32 v[62:63], v[62:63], v[64:65]
	v_pk_add_f32 v[60:61], v[60:61], v[68:69]
	v_pk_add_f32 v[64:65], v[58:59], v[66:67]
	v_pk_add_f32 v[58:59], v[56:57], v[70:71]
	v_cvt_pk_bf16_f32 v56, v60, v61
	v_cvt_pk_bf16_f32 v57, v62, v63
	v_lshl_add_u64 v[66:67], s[34:35], 0, v[80:81]
	v_cvt_pk_bf16_f32 v58, v58, v59
	v_cvt_pk_bf16_f32 v59, v64, v65
	v_mov_b32_e32 v60, v168
	v_mov_b32_e32 v61, v169
	v_mov_b32_e32 v62, v170
	v_mov_b32_e32 v63, v171
	v_lshl_add_u64 v[64:65], v[138:139], 0, s[60:61]
	global_store_dwordx4 v[66:67], v[56:59], off
	s_nop 3
	s_nop 0
	v_lshl_add_u64 v[68:69], s[6:7], 0, v[64:65]
	v_lshlrev_b32_e32 v56, 16, v60
	v_and_b32_e32 v57, 0xffff0000, v60
	v_lshlrev_b32_e32 v58, 16, v61
	v_and_b32_e32 v59, 0xffff0000, v61
	v_lshlrev_b32_e32 v60, 16, v62
	v_and_b32_e32 v61, 0xffff0000, v62
	v_lshlrev_b32_e32 v62, 16, v63
	v_and_b32_e32 v63, 0xffff0000, v63
	v_pk_add_f32 v[52:53], v[52:53], v[56:57]
	v_pk_add_f32 v[56:57], v[50:51], v[62:63]
	v_pk_add_f32 v[50:51], v[48:49], v[60:61]
	v_pk_add_f32 v[54:55], v[54:55], v[58:59]
	v_cvt_pk_bf16_f32 v48, v52, v53
	s_nop 0
	v_cvt_pk_bf16_f32 v49, v54, v55
	v_cvt_pk_bf16_f32 v50, v50, v51
	v_cvt_pk_bf16_f32 v51, v56, v57
	global_store_dwordx4 v[66:67], v[48:51], off offset:256
	s_nop 3
	s_nop 1
	v_mov_b32_e32 v48, v172
	v_mov_b32_e32 v49, v173
	v_mov_b32_e32 v50, v174
	v_mov_b32_e32 v51, v175
	v_lshlrev_b32_e32 v52, 16, v48
	v_and_b32_e32 v53, 0xffff0000, v48
	v_lshlrev_b32_e32 v48, 16, v49
	v_and_b32_e32 v49, 0xffff0000, v49
	v_lshlrev_b32_e32 v54, 16, v50
	v_and_b32_e32 v55, 0xffff0000, v50
	v_lshlrev_b32_e32 v50, 16, v51
	v_and_b32_e32 v51, 0xffff0000, v51
	v_pk_add_f32 v[46:47], v[46:47], v[48:49]
	v_pk_add_f32 v[44:45], v[44:45], v[52:53]
	v_pk_add_f32 v[48:49], v[42:43], v[50:51]
	v_pk_add_f32 v[42:43], v[40:41], v[54:55]
	v_cvt_pk_bf16_f32 v40, v44, v45
	v_cvt_pk_bf16_f32 v41, v46, v47
	v_lshl_add_u64 v[50:51], s[34:35], 0, v[64:65]
	v_cvt_pk_bf16_f32 v42, v42, v43
	v_cvt_pk_bf16_f32 v43, v48, v49
	v_mov_b32_e32 v44, v176
	v_mov_b32_e32 v45, v177
	v_mov_b32_e32 v46, v178
	v_mov_b32_e32 v47, v179
	v_lshl_add_u64 v[48:49], v[138:139], 0, s[38:39]
	global_store_dwordx4 v[50:51], v[40:43], off
	s_nop 3
	v_lshl_add_u64 v[52:53], s[6:7], 0, v[48:49]
	s_mov_b64 s[38:39], 0xb0000
	v_lshlrev_b32_e32 v40, 16, v44
	v_and_b32_e32 v41, 0xffff0000, v44
	v_lshlrev_b32_e32 v42, 16, v45
	v_and_b32_e32 v43, 0xffff0000, v45
	v_lshlrev_b32_e32 v44, 16, v46
	v_and_b32_e32 v45, 0xffff0000, v46
	v_lshlrev_b32_e32 v46, 16, v47
	v_and_b32_e32 v47, 0xffff0000, v47
	v_pk_add_f32 v[36:37], v[36:37], v[40:41]
	v_pk_add_f32 v[40:41], v[34:35], v[46:47]
	v_pk_add_f32 v[34:35], v[32:33], v[44:45]
	v_pk_add_f32 v[38:39], v[38:39], v[42:43]
	v_cvt_pk_bf16_f32 v32, v36, v37
	s_nop 0
	v_cvt_pk_bf16_f32 v33, v38, v39
	v_cvt_pk_bf16_f32 v34, v34, v35
	v_cvt_pk_bf16_f32 v35, v40, v41
	global_store_dwordx4 v[50:51], v[32:35], off offset:256
	s_nop 3
	s_nop 1
	v_mov_b32_e32 v32, v180
	v_mov_b32_e32 v33, v181
	v_mov_b32_e32 v34, v182
	v_mov_b32_e32 v35, v183
	v_lshlrev_b32_e32 v36, 16, v32
	v_and_b32_e32 v37, 0xffff0000, v32
	v_lshlrev_b32_e32 v32, 16, v33
	v_and_b32_e32 v33, 0xffff0000, v33
	v_lshlrev_b32_e32 v38, 16, v34
	v_and_b32_e32 v39, 0xffff0000, v34
	v_lshlrev_b32_e32 v34, 16, v35
	v_and_b32_e32 v35, 0xffff0000, v35
	v_pk_add_f32 v[30:31], v[30:31], v[32:33]
	v_pk_add_f32 v[28:29], v[28:29], v[36:37]
	v_pk_add_f32 v[32:33], v[26:27], v[34:35]
	v_pk_add_f32 v[26:27], v[24:25], v[38:39]
	v_cvt_pk_bf16_f32 v24, v28, v29
	v_cvt_pk_bf16_f32 v25, v30, v31
	v_lshl_add_u64 v[34:35], s[34:35], 0, v[48:49]
	v_cvt_pk_bf16_f32 v26, v26, v27
	v_cvt_pk_bf16_f32 v27, v32, v33
	v_mov_b32_e32 v28, v188
	v_mov_b32_e32 v29, v189
	v_mov_b32_e32 v30, v190
	v_mov_b32_e32 v31, v191
	v_lshl_add_u64 v[32:33], v[138:139], 0, s[38:39]
	global_store_dwordx4 v[34:35], v[24:27], off
	s_nop 3
	s_nop 0
	v_lshl_add_u64 v[36:37], s[6:7], 0, v[32:33]
	v_lshlrev_b32_e32 v24, 16, v28
	v_and_b32_e32 v25, 0xffff0000, v28
	v_lshlrev_b32_e32 v26, 16, v29
	v_and_b32_e32 v27, 0xffff0000, v29
	v_lshlrev_b32_e32 v28, 16, v30
	v_and_b32_e32 v29, 0xffff0000, v30
	v_lshlrev_b32_e32 v30, 16, v31
	v_and_b32_e32 v31, 0xffff0000, v31
	v_pk_add_f32 v[20:21], v[20:21], v[24:25]
	v_pk_add_f32 v[24:25], v[18:19], v[30:31]
	v_pk_add_f32 v[18:19], v[16:17], v[28:29]
	v_pk_add_f32 v[22:23], v[22:23], v[26:27]
	v_cvt_pk_bf16_f32 v16, v20, v21
	s_nop 0
	v_cvt_pk_bf16_f32 v17, v22, v23
	v_cvt_pk_bf16_f32 v18, v18, v19
	v_cvt_pk_bf16_f32 v19, v24, v25
	global_store_dwordx4 v[34:35], v[16:19], off offset:256
	s_nop 3
	s_nop 1
	v_mov_b32_e32 v16, v192
	v_mov_b32_e32 v17, v193
	v_mov_b32_e32 v18, v194
	v_mov_b32_e32 v19, v195
	v_lshlrev_b32_e32 v20, 16, v16
	v_and_b32_e32 v21, 0xffff0000, v16
	v_lshlrev_b32_e32 v16, 16, v17
	v_and_b32_e32 v17, 0xffff0000, v17
	v_lshlrev_b32_e32 v22, 16, v18
	v_and_b32_e32 v23, 0xffff0000, v18
	v_lshlrev_b32_e32 v18, 16, v19
	v_and_b32_e32 v19, 0xffff0000, v19
	v_pk_add_f32 v[14:15], v[14:15], v[16:17]
	v_pk_add_f32 v[12:13], v[12:13], v[20:21]
	v_pk_add_f32 v[16:17], v[10:11], v[18:19]
	v_pk_add_f32 v[10:11], v[8:9], v[22:23]
	v_cvt_pk_bf16_f32 v8, v12, v13
	v_cvt_pk_bf16_f32 v9, v14, v15
	s_nop 0
	v_cvt_pk_bf16_f32 v10, v10, v11
	v_cvt_pk_bf16_f32 v11, v16, v17
	v_mov_b32_e32 v12, v196
	v_mov_b32_e32 v13, v197
	v_mov_b32_e32 v14, v198
	v_mov_b32_e32 v15, v199
	v_lshl_add_u64 v[16:17], s[34:35], 0, v[32:33]
	global_store_dwordx4 v[16:17], v[8:11], off
	s_nop 3
	s_nop 0
	s_nop 0
	v_lshlrev_b32_e32 v8, 16, v12
	v_and_b32_e32 v9, 0xffff0000, v12
	v_lshlrev_b32_e32 v10, 16, v13
	v_and_b32_e32 v11, 0xffff0000, v13
	v_lshlrev_b32_e32 v12, 16, v14
	v_and_b32_e32 v13, 0xffff0000, v14
	v_lshlrev_b32_e32 v14, 16, v15
	v_and_b32_e32 v15, 0xffff0000, v15
	v_pk_add_f32 v[4:5], v[4:5], v[8:9]
	v_pk_add_f32 v[8:9], v[2:3], v[14:15]
	v_pk_add_f32 v[2:3], v[0:1], v[12:13]
	v_pk_add_f32 v[6:7], v[6:7], v[10:11]
	v_cvt_pk_bf16_f32 v0, v4, v5
	s_nop 0
	v_cvt_pk_bf16_f32 v1, v6, v7
	v_cvt_pk_bf16_f32 v2, v2, v3
	v_cvt_pk_bf16_f32 v3, v8, v9
	global_store_dwordx4 v[16:17], v[0:3], off offset:256
	s_nop 3
	s_cbranch_vccnz .LBB0_127
	s_andn2_b64 vcc, exec, s[16:17]
	v_mov_b32 v0, 0
	s_cbranch_vccnz .LBB0_126
	s_barrier
	s_branch .LBB0_126

; #define GAS __attribute__((address_space(1)))
; __device__ __forceinline__ unsigned cvt_pk_bf16(float lo, float hi) { unsigned r; asm volatile("v_cvt_pk_bf16_f32 %0, %1, %2" : "=v"(r) : "v"(lo), "v"(hi)); return r; }
;     __device__ __forceinline__ void operator()(const f32x4 (&acc)[2][2][4][2], const Unit& u, int wr, int wc, int fr, int fq) const {
;     ...
;             const int cb = u.pn * BM + bj * HALF + wc * 32, d = cb % 192; const bool rope = d >= 128; const int j0 = ((d - 128) >> 1) + 4 * fq;
; #pragma unroll
;             for (int ai = 0; ai < 2; ++ai)
; #pragma unroll
;                 for (int m = 0; m < 4; ++m) { const int r = row0 + ai * HALF + m * 16; const float s = *(const GAS float*)(rs + r) * 0.10411754831265403f;
;                     f32x4 v0 = acc[ai][bj][m][0] * s, v1 = acc[ai][bj][m][1] * s;
;                     if (rope) { const f32x4 c4 = *(const GAS f32x4*)(cs + (size_t)r * 32 + j0), s4 = *(const GAS f32x4*)(sn + (size_t)r * 32 + j0);
;                         f32x4 a, b; a[0] = v0[0] * c4[0] - v0[1] * s4[0]; a[1] = v0[0] * s4[0] + v0[1] * c4[0]; a[2] = v0[2] * c4[1] - v0[3] * s4[1]; a[3] = v0[2] * s4[1] + v0[3] * c4[1];
;                         b[0] = v1[0] * c4[2] - v1[1] * s4[2]; b[1] = v1[0] * s4[2] + v1[1] * c4[2]; b[2] = v1[2] * c4[3] - v1[3] * s4[3]; b[3] = v1[2] * s4[3] + v1[3] * c4[3]; v0 = a; v1 = b; }
;                     u32x4 w; w.x = cvt_pk_bf16(v0[0], v0[1]); w.y = cvt_pk_bf16(v0[2], v0[3]); w.z = cvt_pk_bf16(v1[0], v1[1]); w.w = cvt_pk_bf16(v1[2], v1[3]);
;                     *(GAS u32x4*)(O + (size_t)r * QW + col0 + bj * HALF) = w; }
.LBB0_545:
	v_or_b32_e32 v142, s38, v152
	v_cvt_pk_bf16_f32 v156, v144, v145
	v_cvt_pk_bf16_f32 v157, v148, v149
	v_cvt_pk_bf16_f32 v158, v124, v125
	v_mov_b64_e32 v[124:125], s[46:47]
	s_movk_i32 s38, 0xc00
	v_ashrrev_i32_e32 v143, 31, v142
	v_mad_i64_i32 v[124:125], s[38:39], v140, s38, v[124:125]
	v_lshl_add_u64 v[124:125], v[142:143], 1, v[124:125]
	v_cvt_pk_bf16_f32 v159, v146, v147
	global_store_dwordx4 v[124:125], v[156:159], off
	s_nop 3
	v_mov_b32_e32 v141, v193
	v_or_b32_e32 v144, 16, v140
	v_ashrrev_i32_e32 v145, 31, v144
	s_andn2_b64 vcc, exec, s[50:51]
	v_mul_f32_e32 v156, 0x3dd53b95, v141
	v_pk_mul_f32 v[148:149], v[118:119], v[156:157] op_sel_hi:[1,0]
	v_pk_mul_f32 v[118:119], v[116:117], v[156:157] op_sel_hi:[1,0]
	v_pk_mul_f32 v[146:147], v[114:115], v[156:157] op_sel_hi:[1,0]
	v_pk_mul_f32 v[116:117], v[112:113], v[156:157] op_sel_hi:[1,0]
	v_cndmask_b32_e64 v112, 0, 1, s[50:51]
	v_lshlrev_b64 v[114:115], 7, v[144:145]
	v_cmp_ne_u32_e64 s[38:39], 1, v112
	v_lshl_add_u64 v[112:113], s[16:17], 0, v[114:115]
	v_lshl_add_u64 v[114:115], s[18:19], 0, v[114:115]
	s_cbranch_vccnz .LBB0_547
	v_lshl_add_u64 v[156:157], v[112:113], 0, v[126:127]
	v_lshl_add_u64 v[160:161], v[114:115], 0, v[126:127]
	global_load_dwordx4 v[156:159], v[156:157], off
	s_nop 0
	global_load_dwordx4 v[160:163], v[160:161], off
	s_waitcnt vmcnt(0)
	v_pk_mul_f32 v[166:167], v[118:119], v[156:157]
	v_pk_mul_f32 v[164:165], v[118:119], v[160:161] op_sel:[1,0] op_sel_hi:[0,0]
	v_pk_fma_f32 v[118:119], v[118:119], v[156:157], v[164:165] op_sel_hi:[1,0,1]
	v_mov_b32_e32 v160, v157
	v_mul_f32_e32 v118, v149, v161
	v_pk_fma_f32 v[168:169], v[148:149], v[160:161], v[118:119] op_sel_hi:[1,1,0] neg_lo:[0,0,1] neg_hi:[0,0,1]
	v_mov_b32_e32 v156, v161
	v_mul_f32_e32 v118, v149, v157
	v_pk_fma_f32 v[156:157], v[148:149], v[156:157], v[118:119] op_sel_hi:[1,1,0]
	v_pk_mul_f32 v[148:149], v[116:117], v[162:163] op_sel:[1,0] op_sel_hi:[0,0]
	v_pk_mul_f32 v[160:161], v[116:117], v[158:159]
	v_pk_fma_f32 v[116:117], v[116:117], v[158:159], v[148:149] op_sel_hi:[1,0,1]
	v_mov_b32_e32 v162, v159
	v_mul_f32_e32 v116, v147, v163
	v_pk_fma_f32 v[170:171], v[146:147], v[162:163], v[116:117] op_sel_hi:[1,1,0] neg_lo:[0,0,1] neg_hi:[0,0,1]
	v_mov_b32_e32 v158, v163
	v_mul_f32_e32 v116, v147, v159
	v_pk_fma_f32 v[158:159], v[146:147], v[158:159], v[116:117] op_sel_hi:[1,1,0]
	v_sub_f32_e32 v118, v166, v164
	v_sub_f32_e32 v116, v160, v148
	v_mov_b32_e32 v148, v168
	v_mov_b32_e32 v149, v156
	v_mov_b32_e32 v146, v170
	v_mov_b32_e32 v147, v158
.LBB0_547:
	v_cvt_pk_bf16_f32 v156, v118, v119
	v_cvt_pk_bf16_f32 v157, v148, v149
	v_cvt_pk_bf16_f32 v158, v116, v117
	v_mov_b64_e32 v[116:117], s[46:47]
	s_movk_i32 s42, 0xc00
	v_mad_i64_i32 v[116:117], s[50:51], v144, s42, v[116:117]
	v_lshl_add_u64 v[118:119], v[142:143], 1, v[116:117]
	v_cvt_pk_bf16_f32 v159, v146, v147
	global_store_dwordx4 v[118:119], v[156:159], off
	s_nop 3
	v_mov_b32_e32 v141, v194
	v_or_b32_e32 v144, 32, v140
	v_ashrrev_i32_e32 v145, 31, v144
	v_lshlrev_b64 v[148:149], 7, v[144:145]
	s_and_b64 vcc, exec, s[38:39]
	v_lshl_add_u64 v[116:117], s[16:17], 0, v[148:149]
	v_mul_f32_e32 v156, 0x3dd53b95, v141
	v_pk_mul_f32 v[146:147], v[110:111], v[156:157] op_sel_hi:[1,0]
	v_pk_mul_f32 v[108:109], v[108:109], v[156:157] op_sel_hi:[1,0]
	v_pk_mul_f32 v[110:111], v[106:107], v[156:157] op_sel_hi:[1,0]
	v_pk_mul_f32 v[106:107], v[104:105], v[156:157] op_sel_hi:[1,0]
	v_lshl_add_u64 v[104:105], s[18:19], 0, v[148:149]
	s_cbranch_vccnz .LBB0_549
	v_lshl_add_u64 v[148:149], v[116:117], 0, v[126:127]
	global_load_dwordx4 v[156:159], v[148:149], off
	v_lshl_add_u64 v[148:149], v[104:105], 0, v[126:127]
	global_load_dwordx4 v[160:163], v[148:149], off
	s_waitcnt vmcnt(0)
	v_pk_mul_f32 v[164:165], v[108:109], v[156:157]
	v_pk_mul_f32 v[148:149], v[108:109], v[160:161] op_sel:[1,0] op_sel_hi:[0,0]
	v_pk_fma_f32 v[108:109], v[108:109], v[156:157], v[148:149] op_sel_hi:[1,0,1]
	v_mov_b32_e32 v160, v157
	v_mul_f32_e32 v108, v147, v161
	v_pk_fma_f32 v[166:167], v[146:147], v[160:161], v[108:109] op_sel_hi:[1,1,0] neg_lo:[0,0,1] neg_hi:[0,0,1]
	v_mov_b32_e32 v156, v161
	v_mul_f32_e32 v108, v147, v157
	v_pk_fma_f32 v[156:157], v[146:147], v[156:157], v[108:109] op_sel_hi:[1,1,0]
	v_pk_mul_f32 v[146:147], v[106:107], v[162:163] op_sel:[1,0] op_sel_hi:[0,0]
	v_pk_mul_f32 v[160:161], v[106:107], v[158:159]
	v_pk_fma_f32 v[106:107], v[106:107], v[158:159], v[146:147] op_sel_hi:[1,0,1]
	v_mov_b32_e32 v162, v159
	v_mul_f32_e32 v106, v111, v163
	v_pk_fma_f32 v[168:169], v[110:111], v[162:163], v[106:107] op_sel_hi:[1,1,0] neg_lo:[0,0,1] neg_hi:[0,0,1]
	v_mov_b32_e32 v158, v163
	v_mul_f32_e32 v106, v111, v159
	v_pk_fma_f32 v[158:159], v[110:111], v[158:159], v[106:107] op_sel_hi:[1,1,0]
	v_sub_f32_e32 v108, v164, v148
	v_sub_f32_e32 v106, v160, v146
	v_mov_b32_e32 v146, v166
	v_mov_b32_e32 v147, v156
	v_mov_b32_e32 v110, v168
	v_mov_b32_e32 v111, v158
; #define GAS __attribute__((address_space(1)))
; __device__ __forceinline__ unsigned cvt_pk_bf16(float lo, float hi) { unsigned r; asm volatile("v_cvt_pk_bf16_f32 %0, %1, %2" : "=v"(r) : "v"(lo), "v"(hi)); return r; }
;     __device__ __forceinline__ void operator()(const f32x4 (&acc)[2][2][4][2], const Unit& u, int wr, int wc, int fr, int fq) const {
;     ...
;             const int cb = u.pn * BM + bj * HALF + wc * 32, d = cb % 192; const bool rope = d >= 128; const int j0 = ((d - 128) >> 1) + 4 * fq;
; #pragma unroll
;             for (int ai = 0; ai < 2; ++ai)
; #pragma unroll
;                 for (int m = 0; m < 4; ++m) { const int r = row0 + ai * HALF + m * 16; const float s = *(const GAS float*)(rs + r) * 0.10411754831265403f;
;                     f32x4 v0 = acc[ai][bj][m][0] * s, v1 = acc[ai][bj][m][1] * s;
;                     if (rope) { const f32x4 c4 = *(const GAS f32x4*)(cs + (size_t)r * 32 + j0), s4 = *(const GAS f32x4*)(sn + (size_t)r * 32 + j0);
;                         f32x4 a, b; a[0] = v0[0] * c4[0] - v0[1] * s4[0]; a[1] = v0[0] * s4[0] + v0[1] * c4[0]; a[2] = v0[2] * c4[1] - v0[3] * s4[1]; a[3] = v0[2] * s4[1] + v0[3] * c4[1];
;                         b[0] = v1[0] * c4[2] - v1[1] * s4[2]; b[1] = v1[0] * s4[2] + v1[1] * c4[2]; b[2] = v1[2] * c4[3] - v1[3] * s4[3]; b[3] = v1[2] * s4[3] + v1[3] * c4[3]; v0 = a; v1 = b; }
;                     u32x4 w; w.x = cvt_pk_bf16(v0[0], v0[1]); w.y = cvt_pk_bf16(v0[2], v0[3]); w.z = cvt_pk_bf16(v1[0], v1[1]); w.w = cvt_pk_bf16(v1[2], v1[3]);
;                     *(GAS u32x4*)(O + (size_t)r * QW + col0 + bj * HALF) = w; }
.LBB0_549:
	v_cvt_pk_bf16_f32 v156, v108, v109
	v_cvt_pk_bf16_f32 v157, v146, v147
	v_cvt_pk_bf16_f32 v158, v106, v107
	v_mov_b64_e32 v[106:107], s[46:47]
	v_mad_i64_i32 v[106:107], s[50:51], v144, s42, v[106:107]
	v_lshl_add_u64 v[108:109], v[142:143], 1, v[106:107]
	v_cvt_pk_bf16_f32 v159, v110, v111
	global_store_dwordx4 v[108:109], v[156:159], off
	s_nop 3
	v_mov_b32_e32 v141, v195
	v_or_b32_e32 v110, 48, v140
	v_ashrrev_i32_e32 v111, 31, v110
	v_lshlrev_b64 v[146:147], 7, v[110:111]
	s_and_b64 vcc, exec, s[38:39]
	v_lshl_add_u64 v[106:107], s[16:17], 0, v[146:147]
	v_mul_f32_e32 v148, 0x3dd53b95, v141
	v_pk_mul_f32 v[144:145], v[102:103], v[148:149] op_sel_hi:[1,0]
	v_pk_mul_f32 v[100:101], v[100:101], v[148:149] op_sel_hi:[1,0]
	v_pk_mul_f32 v[102:103], v[98:99], v[148:149] op_sel_hi:[1,0]
	v_pk_mul_f32 v[98:99], v[96:97], v[148:149] op_sel_hi:[1,0]
	v_lshl_add_u64 v[96:97], s[18:19], 0, v[146:147]
	s_cbranch_vccnz .LBB0_551
	v_lshl_add_u64 v[146:147], v[106:107], 0, v[126:127]
	v_lshl_add_u64 v[156:157], v[96:97], 0, v[126:127]
	global_load_dwordx4 v[146:149], v[146:147], off
	s_nop 0
	global_load_dwordx4 v[156:159], v[156:157], off
	s_waitcnt vmcnt(0)
	v_pk_mul_f32 v[162:163], v[100:101], v[146:147]
	v_pk_mul_f32 v[160:161], v[100:101], v[156:157] op_sel:[1,0] op_sel_hi:[0,0]
	v_pk_fma_f32 v[100:101], v[100:101], v[146:147], v[160:161] op_sel_hi:[1,0,1]
	v_mov_b32_e32 v156, v147
	v_mul_f32_e32 v100, v145, v157
	v_pk_fma_f32 v[164:165], v[144:145], v[156:157], v[100:101] op_sel_hi:[1,1,0] neg_lo:[0,0,1] neg_hi:[0,0,1]
	v_mov_b32_e32 v146, v157
	v_mul_f32_e32 v100, v145, v147
	v_pk_fma_f32 v[146:147], v[144:145], v[146:147], v[100:101] op_sel_hi:[1,1,0]
	v_pk_mul_f32 v[144:145], v[98:99], v[158:159] op_sel:[1,0] op_sel_hi:[0,0]
	v_pk_mul_f32 v[156:157], v[98:99], v[148:149]
	v_pk_fma_f32 v[98:99], v[98:99], v[148:149], v[144:145] op_sel_hi:[1,0,1]
	v_mov_b32_e32 v158, v149
	v_mul_f32_e32 v98, v103, v159
	v_pk_fma_f32 v[166:167], v[102:103], v[158:159], v[98:99] op_sel_hi:[1,1,0] neg_lo:[0,0,1] neg_hi:[0,0,1]
	v_mov_b32_e32 v148, v159
	v_mul_f32_e32 v98, v103, v149
	v_pk_fma_f32 v[148:149], v[102:103], v[148:149], v[98:99] op_sel_hi:[1,1,0]
	v_sub_f32_e32 v100, v162, v160
	v_sub_f32_e32 v98, v156, v144
	v_mov_b32_e32 v144, v164
	v_mov_b32_e32 v145, v146
	v_mov_b32_e32 v102, v166
	v_mov_b32_e32 v103, v148
.LBB0_551:
	v_cvt_pk_bf16_f32 v146, v100, v101
	v_cvt_pk_bf16_f32 v147, v144, v145
	v_cvt_pk_bf16_f32 v148, v98, v99
	v_mov_b64_e32 v[98:99], s[46:47]
	v_mad_i64_i32 v[98:99], s[50:51], v110, s42, v[98:99]
	v_lshl_add_u64 v[100:101], v[142:143], 1, v[98:99]
	v_cvt_pk_bf16_f32 v149, v102, v103
	global_store_dwordx4 v[100:101], v[146:149], off
	s_nop 3
	v_mov_b32_e32 v110, v196
	v_add_u32_e32 v102, 0x80, v140
	v_ashrrev_i32_e32 v103, 31, v102
	v_lshlrev_b64 v[144:145], 7, v[102:103]
	s_and_b64 vcc, exec, s[38:39]
	v_lshl_add_u64 v[98:99], s[16:17], 0, v[144:145]
	v_mul_f32_e32 v146, 0x3dd53b95, v110
	v_pk_mul_f32 v[110:111], v[94:95], v[146:147] op_sel_hi:[1,0]
	v_pk_mul_f32 v[92:93], v[92:93], v[146:147] op_sel_hi:[1,0]
	v_pk_mul_f32 v[94:95], v[90:91], v[146:147] op_sel_hi:[1,0]
	v_pk_mul_f32 v[90:91], v[88:89], v[146:147] op_sel_hi:[1,0]
	v_lshl_add_u64 v[88:89], s[18:19], 0, v[144:145]
	s_cbranch_vccnz .LBB0_553
	v_lshl_add_u64 v[144:145], v[98:99], 0, v[126:127]
	v_lshl_add_u64 v[148:149], v[88:89], 0, v[126:127]
	global_load_dwordx4 v[144:147], v[144:145], off
	s_nop 0
	global_load_dwordx4 v[156:159], v[148:149], off
	s_waitcnt vmcnt(0)
	v_pk_mul_f32 v[160:161], v[92:93], v[144:145]
	v_pk_mul_f32 v[148:149], v[92:93], v[156:157] op_sel:[1,0] op_sel_hi:[0,0]
	v_pk_fma_f32 v[92:93], v[92:93], v[144:145], v[148:149] op_sel_hi:[1,0,1]
	v_mov_b32_e32 v156, v145
	v_mul_f32_e32 v92, v111, v157
	v_pk_fma_f32 v[162:163], v[110:111], v[156:157], v[92:93] op_sel_hi:[1,1,0] neg_lo:[0,0,1] neg_hi:[0,0,1]
	v_mov_b32_e32 v144, v157
	v_mul_f32_e32 v92, v111, v145
	v_pk_fma_f32 v[144:145], v[110:111], v[144:145], v[92:93] op_sel_hi:[1,1,0]
	v_pk_mul_f32 v[110:111], v[90:91], v[158:159] op_sel:[1,0] op_sel_hi:[0,0]
	v_pk_mul_f32 v[156:157], v[90:91], v[146:147]
	v_pk_fma_f32 v[90:91], v[90:91], v[146:147], v[110:111] op_sel_hi:[1,0,1]
	v_mov_b32_e32 v158, v147
	v_mul_f32_e32 v90, v95, v159
	v_pk_fma_f32 v[164:165], v[94:95], v[158:159], v[90:91] op_sel_hi:[1,1,0] neg_lo:[0,0,1] neg_hi:[0,0,1]
	v_mov_b32_e32 v146, v159
	v_mul_f32_e32 v90, v95, v147
	v_pk_fma_f32 v[146:147], v[94:95], v[146:147], v[90:91] op_sel_hi:[1,1,0]
	v_sub_f32_e32 v92, v160, v148
	v_sub_f32_e32 v90, v156, v110
	v_mov_b32_e32 v110, v162
	v_mov_b32_e32 v111, v144
	v_mov_b32_e32 v94, v164
	v_mov_b32_e32 v95, v146
; #define GAS __attribute__((address_space(1)))
; __device__ __forceinline__ unsigned cvt_pk_bf16(float lo, float hi) { unsigned r; asm volatile("v_cvt_pk_bf16_f32 %0, %1, %2" : "=v"(r) : "v"(lo), "v"(hi)); return r; }
;     __device__ __forceinline__ void operator()(const f32x4 (&acc)[2][2][4][2], const Unit& u, int wr, int wc, int fr, int fq) const {
;     ...
;             const int cb = u.pn * BM + bj * HALF + wc * 32, d = cb % 192; const bool rope = d >= 128; const int j0 = ((d - 128) >> 1) + 4 * fq;
; #pragma unroll
;             for (int ai = 0; ai < 2; ++ai)
; #pragma unroll
;                 for (int m = 0; m < 4; ++m) { const int r = row0 + ai * HALF + m * 16; const float s = *(const GAS float*)(rs + r) * 0.10411754831265403f;
;                     f32x4 v0 = acc[ai][bj][m][0] * s, v1 = acc[ai][bj][m][1] * s;
;                     if (rope) { const f32x4 c4 = *(const GAS f32x4*)(cs + (size_t)r * 32 + j0), s4 = *(const GAS f32x4*)(sn + (size_t)r * 32 + j0);
;                         f32x4 a, b; a[0] = v0[0] * c4[0] - v0[1] * s4[0]; a[1] = v0[0] * s4[0] + v0[1] * c4[0]; a[2] = v0[2] * c4[1] - v0[3] * s4[1]; a[3] = v0[2] * s4[1] + v0[3] * c4[1];
;                         b[0] = v1[0] * c4[2] - v1[1] * s4[2]; b[1] = v1[0] * s4[2] + v1[1] * c4[2]; b[2] = v1[2] * c4[3] - v1[3] * s4[3]; b[3] = v1[2] * s4[3] + v1[3] * c4[3]; v0 = a; v1 = b; }
;                     u32x4 w; w.x = cvt_pk_bf16(v0[0], v0[1]); w.y = cvt_pk_bf16(v0[2], v0[3]); w.z = cvt_pk_bf16(v1[0], v1[1]); w.w = cvt_pk_bf16(v1[2], v1[3]);
;                     *(GAS u32x4*)(O + (size_t)r * QW + col0 + bj * HALF) = w; }
.LBB0_553:
	v_cvt_pk_bf16_f32 v144, v92, v93
	v_cvt_pk_bf16_f32 v145, v110, v111
	v_cvt_pk_bf16_f32 v146, v90, v91
	v_mov_b64_e32 v[90:91], s[46:47]
	v_mad_i64_i32 v[90:91], s[50:51], v102, s42, v[90:91]
	v_lshl_add_u64 v[92:93], v[142:143], 1, v[90:91]
	v_cvt_pk_bf16_f32 v147, v94, v95
	global_store_dwordx4 v[92:93], v[144:147], off
	s_nop 3
	v_mov_b32_e32 v102, v197
	v_add_u32_e32 v94, 0x90, v140
	v_ashrrev_i32_e32 v95, 31, v94
	v_lshlrev_b64 v[110:111], 7, v[94:95]
	s_and_b64 vcc, exec, s[38:39]
	v_lshl_add_u64 v[90:91], s[16:17], 0, v[110:111]
	v_mul_f32_e32 v144, 0x3dd53b95, v102
	v_pk_mul_f32 v[102:103], v[86:87], v[144:145] op_sel_hi:[1,0]
	v_pk_mul_f32 v[84:85], v[84:85], v[144:145] op_sel_hi:[1,0]
	v_pk_mul_f32 v[86:87], v[82:83], v[144:145] op_sel_hi:[1,0]
	v_pk_mul_f32 v[82:83], v[80:81], v[144:145] op_sel_hi:[1,0]
	v_lshl_add_u64 v[80:81], s[18:19], 0, v[110:111]
	s_cbranch_vccnz .LBB0_555
	v_lshl_add_u64 v[110:111], v[90:91], 0, v[126:127]
	global_load_dwordx4 v[144:147], v[110:111], off
	v_lshl_add_u64 v[110:111], v[80:81], 0, v[126:127]
	global_load_dwordx4 v[156:159], v[110:111], off
	s_waitcnt vmcnt(0)
	v_pk_mul_f32 v[148:149], v[84:85], v[144:145]
	v_pk_mul_f32 v[110:111], v[84:85], v[156:157] op_sel:[1,0] op_sel_hi:[0,0]
	v_pk_fma_f32 v[84:85], v[84:85], v[144:145], v[110:111] op_sel_hi:[1,0,1]
	v_mov_b32_e32 v156, v145
	v_mul_f32_e32 v84, v103, v157
	v_pk_fma_f32 v[160:161], v[102:103], v[156:157], v[84:85] op_sel_hi:[1,1,0] neg_lo:[0,0,1] neg_hi:[0,0,1]
	v_mov_b32_e32 v144, v157
	v_mul_f32_e32 v84, v103, v145
	v_pk_fma_f32 v[144:145], v[102:103], v[144:145], v[84:85] op_sel_hi:[1,1,0]
	v_pk_mul_f32 v[102:103], v[82:83], v[158:159] op_sel:[1,0] op_sel_hi:[0,0]
	v_pk_mul_f32 v[156:157], v[82:83], v[146:147]
	v_pk_fma_f32 v[82:83], v[82:83], v[146:147], v[102:103] op_sel_hi:[1,0,1]
	v_mov_b32_e32 v158, v147
	v_mul_f32_e32 v82, v87, v159
	v_pk_fma_f32 v[162:163], v[86:87], v[158:159], v[82:83] op_sel_hi:[1,1,0] neg_lo:[0,0,1] neg_hi:[0,0,1]
	v_mov_b32_e32 v146, v159
	v_mul_f32_e32 v82, v87, v147
	v_pk_fma_f32 v[146:147], v[86:87], v[146:147], v[82:83] op_sel_hi:[1,1,0]
	v_sub_f32_e32 v84, v148, v110
	v_sub_f32_e32 v82, v156, v102
	v_mov_b32_e32 v102, v160
	v_mov_b32_e32 v103, v144
	v_mov_b32_e32 v86, v162
	v_mov_b32_e32 v87, v146
.LBB0_555:
	v_cvt_pk_bf16_f32 v144, v84, v85
	v_cvt_pk_bf16_f32 v145, v102, v103
	v_cvt_pk_bf16_f32 v146, v82, v83
	v_mov_b64_e32 v[82:83], s[46:47]
	v_mad_i64_i32 v[82:83], s[50:51], v94, s42, v[82:83]
	v_lshl_add_u64 v[84:85], v[142:143], 1, v[82:83]
	v_cvt_pk_bf16_f32 v147, v86, v87
	global_store_dwordx4 v[84:85], v[144:147], off
	s_nop 3
	v_mov_b32_e32 v94, v198
	v_add_u32_e32 v86, 0xa0, v140
	v_ashrrev_i32_e32 v87, 31, v86
	v_lshlrev_b64 v[102:103], 7, v[86:87]
	s_and_b64 vcc, exec, s[38:39]
	v_lshl_add_u64 v[82:83], s[16:17], 0, v[102:103]
	v_mul_f32_e32 v110, 0x3dd53b95, v94
	v_pk_mul_f32 v[94:95], v[78:79], v[110:111] op_sel_hi:[1,0]
	v_pk_mul_f32 v[76:77], v[76:77], v[110:111] op_sel_hi:[1,0]
	v_pk_mul_f32 v[78:79], v[74:75], v[110:111] op_sel_hi:[1,0]
	v_pk_mul_f32 v[74:75], v[72:73], v[110:111] op_sel_hi:[1,0]
	v_lshl_add_u64 v[72:73], s[18:19], 0, v[102:103]
	s_cbranch_vccnz .LBB0_557
	v_lshl_add_u64 v[102:103], v[82:83], 0, v[126:127]
	global_load_dwordx4 v[144:147], v[102:103], off
	v_lshl_add_u64 v[102:103], v[72:73], 0, v[126:127]
	global_load_dwordx4 v[156:159], v[102:103], off
	s_waitcnt vmcnt(0)
	v_pk_mul_f32 v[110:111], v[76:77], v[144:145]
	v_pk_mul_f32 v[102:103], v[76:77], v[156:157] op_sel:[1,0] op_sel_hi:[0,0]
	v_pk_fma_f32 v[76:77], v[76:77], v[144:145], v[102:103] op_sel_hi:[1,0,1]
	v_mov_b32_e32 v156, v145
	v_mul_f32_e32 v76, v95, v157
	v_pk_fma_f32 v[148:149], v[94:95], v[156:157], v[76:77] op_sel_hi:[1,1,0] neg_lo:[0,0,1] neg_hi:[0,0,1]
	v_mov_b32_e32 v144, v157
	v_mul_f32_e32 v76, v95, v145
	v_pk_fma_f32 v[144:145], v[94:95], v[144:145], v[76:77] op_sel_hi:[1,1,0]
	v_pk_mul_f32 v[94:95], v[74:75], v[158:159] op_sel:[1,0] op_sel_hi:[0,0]
	v_pk_mul_f32 v[156:157], v[74:75], v[146:147]
	v_pk_fma_f32 v[74:75], v[74:75], v[146:147], v[94:95] op_sel_hi:[1,0,1]
	v_mov_b32_e32 v158, v147
	v_mul_f32_e32 v74, v79, v159
	v_pk_fma_f32 v[160:161], v[78:79], v[158:159], v[74:75] op_sel_hi:[1,1,0] neg_lo:[0,0,1] neg_hi:[0,0,1]
	v_mov_b32_e32 v146, v159
	v_mul_f32_e32 v74, v79, v147
	v_pk_fma_f32 v[146:147], v[78:79], v[146:147], v[74:75] op_sel_hi:[1,1,0]
	v_sub_f32_e32 v76, v110, v102
	v_sub_f32_e32 v74, v156, v94
	v_mov_b32_e32 v94, v148
	v_mov_b32_e32 v95, v144
	v_mov_b32_e32 v78, v160
	v_mov_b32_e32 v79, v146
; #define GAS __attribute__((address_space(1)))
; __device__ __forceinline__ unsigned cvt_pk_bf16(float lo, float hi) { unsigned r; asm volatile("v_cvt_pk_bf16_f32 %0, %1, %2" : "=v"(r) : "v"(lo), "v"(hi)); return r; }
;     __device__ __forceinline__ void operator()(const f32x4 (&acc)[2][2][4][2], const Unit& u, int wr, int wc, int fr, int fq) const {
;     ...
;             const int cb = u.pn * BM + bj * HALF + wc * 32, d = cb % 192; const bool rope = d >= 128; const int j0 = ((d - 128) >> 1) + 4 * fq;
; #pragma unroll
;             for (int ai = 0; ai < 2; ++ai)
; #pragma unroll
;                 for (int m = 0; m < 4; ++m) { const int r = row0 + ai * HALF + m * 16; const float s = *(const GAS float*)(rs + r) * 0.10411754831265403f;
;                     f32x4 v0 = acc[ai][bj][m][0] * s, v1 = acc[ai][bj][m][1] * s;
;                     if (rope) { const f32x4 c4 = *(const GAS f32x4*)(cs + (size_t)r * 32 + j0), s4 = *(const GAS f32x4*)(sn + (size_t)r * 32 + j0);
;                         f32x4 a, b; a[0] = v0[0] * c4[0] - v0[1] * s4[0]; a[1] = v0[0] * s4[0] + v0[1] * c4[0]; a[2] = v0[2] * c4[1] - v0[3] * s4[1]; a[3] = v0[2] * s4[1] + v0[3] * c4[1];
;                         b[0] = v1[0] * c4[2] - v1[1] * s4[2]; b[1] = v1[0] * s4[2] + v1[1] * c4[2]; b[2] = v1[2] * c4[3] - v1[3] * s4[3]; b[3] = v1[2] * s4[3] + v1[3] * c4[3]; v0 = a; v1 = b; }
;                     u32x4 w; w.x = cvt_pk_bf16(v0[0], v0[1]); w.y = cvt_pk_bf16(v0[2], v0[3]); w.z = cvt_pk_bf16(v1[0], v1[1]); w.w = cvt_pk_bf16(v1[2], v1[3]);
;                     *(GAS u32x4*)(O + (size_t)r * QW + col0 + bj * HALF) = w; }
.LBB0_557:
	v_cvt_pk_bf16_f32 v144, v76, v77
	v_cvt_pk_bf16_f32 v145, v94, v95
	v_cvt_pk_bf16_f32 v146, v74, v75
	v_mov_b64_e32 v[74:75], s[46:47]
	v_mad_i64_i32 v[74:75], s[50:51], v86, s42, v[74:75]
	v_lshl_add_u64 v[76:77], v[142:143], 1, v[74:75]
	v_cvt_pk_bf16_f32 v147, v78, v79
	global_store_dwordx4 v[76:77], v[144:147], off
	s_nop 3
	v_mov_b32_e32 v86, v199
	v_add_u32_e32 v78, 0xb0, v140
	v_ashrrev_i32_e32 v79, 31, v78
	v_lshlrev_b64 v[94:95], 7, v[78:79]
	s_and_b64 vcc, exec, s[38:39]
	v_lshl_add_u64 v[74:75], s[16:17], 0, v[94:95]
	v_mul_f32_e32 v102, 0x3dd53b95, v86
	v_pk_mul_f32 v[86:87], v[70:71], v[102:103] op_sel_hi:[1,0]
	v_pk_mul_f32 v[68:69], v[68:69], v[102:103] op_sel_hi:[1,0]
	v_pk_mul_f32 v[70:71], v[66:67], v[102:103] op_sel_hi:[1,0]
	v_pk_mul_f32 v[66:67], v[64:65], v[102:103] op_sel_hi:[1,0]
	v_lshl_add_u64 v[64:65], s[18:19], 0, v[94:95]
	s_cbranch_vccnz .LBB0_559
	v_lshl_add_u64 v[94:95], v[74:75], 0, v[126:127]
	global_load_dwordx4 v[144:147], v[94:95], off
	v_lshl_add_u64 v[94:95], v[64:65], 0, v[126:127]
	global_load_dwordx4 v[156:159], v[94:95], off
	s_waitcnt vmcnt(0)
	v_pk_mul_f32 v[102:103], v[68:69], v[144:145]
	v_pk_mul_f32 v[140:141], v[66:67], v[146:147]
	v_pk_mul_f32 v[94:95], v[68:69], v[156:157] op_sel:[1,0] op_sel_hi:[0,0]
	v_pk_fma_f32 v[68:69], v[68:69], v[144:145], v[94:95] op_sel_hi:[1,0,1]
	v_mov_b32_e32 v156, v145
	v_mul_f32_e32 v68, v87, v157
	v_pk_fma_f32 v[110:111], v[86:87], v[156:157], v[68:69] op_sel_hi:[1,1,0] neg_lo:[0,0,1] neg_hi:[0,0,1]
	v_mov_b32_e32 v144, v157
	v_mul_f32_e32 v68, v87, v145
	v_pk_fma_f32 v[126:127], v[86:87], v[144:145], v[68:69] op_sel_hi:[1,1,0]
	v_pk_mul_f32 v[86:87], v[66:67], v[158:159] op_sel:[1,0] op_sel_hi:[0,0]
	v_pk_fma_f32 v[66:67], v[66:67], v[146:147], v[86:87] op_sel_hi:[1,0,1]
	v_mov_b32_e32 v158, v147
	v_mul_f32_e32 v66, v71, v159
	v_pk_fma_f32 v[144:145], v[70:71], v[158:159], v[66:67] op_sel_hi:[1,1,0] neg_lo:[0,0,1] neg_hi:[0,0,1]
	v_mov_b32_e32 v146, v159
	v_mul_f32_e32 v66, v71, v147
	v_pk_fma_f32 v[146:147], v[70:71], v[146:147], v[66:67] op_sel_hi:[1,1,0]
	v_sub_f32_e32 v68, v102, v94
	v_sub_f32_e32 v66, v140, v86
	v_mov_b32_e32 v86, v110
	v_mov_b32_e32 v87, v126
	v_mov_b32_e32 v70, v144
	v_mov_b32_e32 v71, v146
.LBB0_559:
	v_cvt_pk_bf16_f32 v144, v68, v69
	v_cvt_pk_bf16_f32 v145, v86, v87
	v_cvt_pk_bf16_f32 v146, v66, v67
	v_mov_b64_e32 v[66:67], s[46:47]
	s_movk_i32 s38, 0xc00
	v_mad_i64_i32 v[66:67], s[38:39], v78, s38, v[66:67]
	v_lshl_add_u64 v[66:67], v[142:143], 1, v[66:67]
	v_cvt_pk_bf16_f32 v147, v70, v71
	global_store_dwordx4 v[66:67], v[144:147], off
	s_nop 3
	v_mov_b32_e32 v68, v192
	s_bitset1_b32 s63, 7
	s_mul_hi_i32 s38, s63, 0x2aaaaaab
	s_lshr_b32 s39, s38, 31
	s_lshr_b32 s38, s38, 5
	s_add_i32 s38, s38, s39
	s_mulk_i32 s38, 0xc0
	s_sub_i32 s38, s63, s38
	s_cmpk_gt_i32 s38, 0x7f
	s_cselect_b64 s[50:51], -1, 0
	s_add_i32 s39, s38, 0xffffff80
	s_ashr_i32 s39, s39, 1
	v_or_b32_e32 v70, s39, v153
	v_ashrrev_i32_e32 v71, 31, v70
	s_cmpk_lt_i32 s38, 0x80
	v_mul_f32_e32 v78, 0x3dd53b95, v68
	v_pk_mul_f32 v[68:69], v[62:63], v[78:79] op_sel_hi:[1,0]
	v_pk_mul_f32 v[60:61], v[60:61], v[78:79] op_sel_hi:[1,0]
	v_pk_mul_f32 v[62:63], v[58:59], v[78:79] op_sel_hi:[1,0]
	v_pk_mul_f32 v[58:59], v[56:57], v[78:79] op_sel_hi:[1,0]
	v_lshlrev_b64 v[56:57], 2, v[70:71]
	s_cbranch_scc1 .LBB0_561
	v_lshl_add_u64 v[70:71], v[120:121], 0, v[56:57]
	global_load_dwordx4 v[140:143], v[70:71], off
	v_lshl_add_u64 v[70:71], v[122:123], 0, v[56:57]
	global_load_dwordx4 v[120:123], v[70:71], off
	s_waitcnt vmcnt(0)
	v_pk_mul_f32 v[78:79], v[60:61], v[140:141]
	v_pk_mul_f32 v[102:103], v[58:59], v[142:143]
	v_pk_mul_f32 v[70:71], v[60:61], v[120:121] op_sel:[1,0] op_sel_hi:[0,0]
	v_pk_fma_f32 v[60:61], v[60:61], v[140:141], v[70:71] op_sel_hi:[1,0,1]
	v_mov_b32_e32 v120, v141
	v_mul_f32_e32 v60, v69, v121
	v_pk_fma_f32 v[86:87], v[68:69], v[120:121], v[60:61] op_sel_hi:[1,1,0] neg_lo:[0,0,1] neg_hi:[0,0,1]
	v_mov_b32_e32 v140, v121
	v_mul_f32_e32 v60, v69, v141
	v_pk_fma_f32 v[94:95], v[68:69], v[140:141], v[60:61] op_sel_hi:[1,1,0]
	v_pk_mul_f32 v[68:69], v[58:59], v[122:123] op_sel:[1,0] op_sel_hi:[0,0]
	v_pk_fma_f32 v[58:59], v[58:59], v[142:143], v[68:69] op_sel_hi:[1,0,1]
	v_mov_b32_e32 v122, v143
	v_mul_f32_e32 v58, v63, v123
	v_pk_fma_f32 v[110:111], v[62:63], v[122:123], v[58:59] op_sel_hi:[1,1,0] neg_lo:[0,0,1] neg_hi:[0,0,1]
	v_mov_b32_e32 v142, v123
	v_mul_f32_e32 v58, v63, v143
	v_pk_fma_f32 v[120:121], v[62:63], v[142:143], v[58:59] op_sel_hi:[1,1,0]
	v_sub_f32_e32 v60, v78, v70
	v_sub_f32_e32 v58, v102, v68
	v_mov_b32_e32 v68, v86
	v_mov_b32_e32 v69, v94
	v_mov_b32_e32 v62, v110
	v_mov_b32_e32 v63, v120
; #define GAS __attribute__((address_space(1)))
; __device__ __forceinline__ unsigned cvt_pk_bf16(float lo, float hi) { unsigned r; asm volatile("v_cvt_pk_bf16_f32 %0, %1, %2" : "=v"(r) : "v"(lo), "v"(hi)); return r; }
;     __device__ __forceinline__ void operator()(const f32x4 (&acc)[2][2][4][2], const Unit& u, int wr, int wc, int fr, int fq) const {
;     ...
;             const int cb = u.pn * BM + bj * HALF + wc * 32, d = cb % 192; const bool rope = d >= 128; const int j0 = ((d - 128) >> 1) + 4 * fq;
; #pragma unroll
;             for (int ai = 0; ai < 2; ++ai)
; #pragma unroll
;                 for (int m = 0; m < 4; ++m) { const int r = row0 + ai * HALF + m * 16; const float s = *(const GAS float*)(rs + r) * 0.10411754831265403f;
;                     f32x4 v0 = acc[ai][bj][m][0] * s, v1 = acc[ai][bj][m][1] * s;
;                     if (rope) { const f32x4 c4 = *(const GAS f32x4*)(cs + (size_t)r * 32 + j0), s4 = *(const GAS f32x4*)(sn + (size_t)r * 32 + j0);
;                         f32x4 a, b; a[0] = v0[0] * c4[0] - v0[1] * s4[0]; a[1] = v0[0] * s4[0] + v0[1] * c4[0]; a[2] = v0[2] * c4[1] - v0[3] * s4[1]; a[3] = v0[2] * s4[1] + v0[3] * c4[1];
;                         b[0] = v1[0] * c4[2] - v1[1] * s4[2]; b[1] = v1[0] * s4[2] + v1[1] * c4[2]; b[2] = v1[2] * c4[3] - v1[3] * s4[3]; b[3] = v1[2] * s4[3] + v1[3] * c4[3]; v0 = a; v1 = b; }
;                     u32x4 w; w.x = cvt_pk_bf16(v0[0], v0[1]); w.y = cvt_pk_bf16(v0[2], v0[3]); w.z = cvt_pk_bf16(v1[0], v1[1]); w.w = cvt_pk_bf16(v1[2], v1[3]);
;                     *(GAS u32x4*)(O + (size_t)r * QW + col0 + bj * HALF) = w; }
.LBB0_561:
	v_cvt_pk_bf16_f32 v120, v60, v61
	v_cvt_pk_bf16_f32 v121, v68, v69
	v_cvt_pk_bf16_f32 v122, v58, v59
	v_cvt_pk_bf16_f32 v123, v62, v63
	global_store_dwordx4 v[124:125], v[120:123], off offset:256
	s_nop 3
	v_mov_b32_e32 v58, v193
	v_cndmask_b32_e64 v59, 0, 1, s[50:51]
	v_cmp_ne_u32_e64 s[38:39], 1, v59
	s_andn2_b64 vcc, exec, s[50:51]
	v_mul_f32_e32 v58, 0x3dd53b95, v58
	v_pk_mul_f32 v[54:55], v[54:55], v[58:59] op_sel_hi:[1,0]
	v_pk_mul_f32 v[52:53], v[52:53], v[58:59] op_sel_hi:[1,0]
	v_pk_mul_f32 v[50:51], v[50:51], v[58:59] op_sel_hi:[1,0]
	v_pk_mul_f32 v[48:49], v[48:49], v[58:59] op_sel_hi:[1,0]
	s_cbranch_vccnz .LBB0_563
	v_lshl_add_u64 v[58:59], v[112:113], 0, v[56:57]
	v_lshl_add_u64 v[62:63], v[114:115], 0, v[56:57]
	global_load_dwordx4 v[58:61], v[58:59], off
	s_nop 0
	global_load_dwordx4 v[68:71], v[62:63], off
	s_waitcnt vmcnt(0)
	v_pk_mul_f32 v[78:79], v[52:53], v[58:59]
	v_pk_mul_f32 v[62:63], v[52:53], v[68:69] op_sel:[1,0] op_sel_hi:[0,0]
	v_pk_fma_f32 v[52:53], v[52:53], v[58:59], v[62:63] op_sel_hi:[1,0,1]
	v_mov_b32_e32 v68, v59
	v_mul_f32_e32 v52, v55, v69
	v_pk_fma_f32 v[86:87], v[54:55], v[68:69], v[52:53] op_sel_hi:[1,1,0] neg_lo:[0,0,1] neg_hi:[0,0,1]
	v_mov_b32_e32 v58, v69
	v_mul_f32_e32 v52, v55, v59
	v_pk_fma_f32 v[58:59], v[54:55], v[58:59], v[52:53] op_sel_hi:[1,1,0]
	v_pk_mul_f32 v[54:55], v[48:49], v[70:71] op_sel:[1,0] op_sel_hi:[0,0]
	v_pk_mul_f32 v[68:69], v[48:49], v[60:61]
	v_pk_fma_f32 v[48:49], v[48:49], v[60:61], v[54:55] op_sel_hi:[1,0,1]
	v_mov_b32_e32 v70, v61
	v_mul_f32_e32 v48, v51, v71
	v_pk_fma_f32 v[94:95], v[50:51], v[70:71], v[48:49] op_sel_hi:[1,1,0] neg_lo:[0,0,1] neg_hi:[0,0,1]
	v_mov_b32_e32 v60, v71
	v_mul_f32_e32 v48, v51, v61
	v_pk_fma_f32 v[60:61], v[50:51], v[60:61], v[48:49] op_sel_hi:[1,1,0]
	v_sub_f32_e32 v52, v78, v62
	v_sub_f32_e32 v48, v68, v54
	v_mov_b32_e32 v54, v86
	v_mov_b32_e32 v55, v58
	v_mov_b32_e32 v50, v94
	v_mov_b32_e32 v51, v60
.LBB0_563:
	v_cvt_pk_bf16_f32 v52, v52, v53
	v_cvt_pk_bf16_f32 v53, v54, v55
	v_cvt_pk_bf16_f32 v54, v48, v49
	v_cvt_pk_bf16_f32 v55, v50, v51
	global_store_dwordx4 v[118:119], v[52:55], off offset:256
	s_nop 3
	v_mov_b32_e32 v48, v194
	s_and_b64 vcc, exec, s[38:39]
	v_mul_f32_e32 v48, 0x3dd53b95, v48
	v_pk_mul_f32 v[46:47], v[46:47], v[48:49] op_sel_hi:[1,0]
	v_pk_mul_f32 v[44:45], v[44:45], v[48:49] op_sel_hi:[1,0]
	v_pk_mul_f32 v[42:43], v[42:43], v[48:49] op_sel_hi:[1,0]
	v_pk_mul_f32 v[40:41], v[40:41], v[48:49] op_sel_hi:[1,0]
	s_cbranch_vccnz .LBB0_565
	v_lshl_add_u64 v[48:49], v[116:117], 0, v[56:57]
	v_lshl_add_u64 v[52:53], v[104:105], 0, v[56:57]
	global_load_dwordx4 v[48:51], v[48:49], off
	s_nop 0
	global_load_dwordx4 v[52:55], v[52:53], off
	s_waitcnt vmcnt(0)
	v_pk_mul_f32 v[60:61], v[44:45], v[48:49]
	v_pk_mul_f32 v[58:59], v[44:45], v[52:53] op_sel:[1,0] op_sel_hi:[0,0]
	v_pk_fma_f32 v[44:45], v[44:45], v[48:49], v[58:59] op_sel_hi:[1,0,1]
	v_mov_b32_e32 v52, v49
	v_mul_f32_e32 v44, v47, v53
	v_pk_fma_f32 v[62:63], v[46:47], v[52:53], v[44:45] op_sel_hi:[1,1,0] neg_lo:[0,0,1] neg_hi:[0,0,1]
	v_mov_b32_e32 v48, v53
	v_mul_f32_e32 v44, v47, v49
	v_pk_fma_f32 v[48:49], v[46:47], v[48:49], v[44:45] op_sel_hi:[1,1,0]
	v_pk_mul_f32 v[46:47], v[40:41], v[54:55] op_sel:[1,0] op_sel_hi:[0,0]
	v_pk_mul_f32 v[52:53], v[40:41], v[50:51]
	v_pk_fma_f32 v[40:41], v[40:41], v[50:51], v[46:47] op_sel_hi:[1,0,1]
	v_mov_b32_e32 v54, v51
	v_mul_f32_e32 v40, v43, v55
	v_pk_fma_f32 v[68:69], v[42:43], v[54:55], v[40:41] op_sel_hi:[1,1,0] neg_lo:[0,0,1] neg_hi:[0,0,1]
	v_mov_b32_e32 v50, v55
	v_mul_f32_e32 v40, v43, v51
	v_pk_fma_f32 v[50:51], v[42:43], v[50:51], v[40:41] op_sel_hi:[1,1,0]
	v_sub_f32_e32 v44, v60, v58
	v_sub_f32_e32 v40, v52, v46
	v_mov_b32_e32 v46, v62
	v_mov_b32_e32 v47, v48
	v_mov_b32_e32 v42, v68
	v_mov_b32_e32 v43, v50
.LBB0_565:
	v_cvt_pk_bf16_f32 v44, v44, v45
	v_cvt_pk_bf16_f32 v45, v46, v47
	v_cvt_pk_bf16_f32 v46, v40, v41
	v_cvt_pk_bf16_f32 v47, v42, v43
	global_store_dwordx4 v[108:109], v[44:47], off offset:256
	s_nop 3
	v_mov_b32_e32 v40, v195
	s_and_b64 vcc, exec, s[38:39]
	v_mul_f32_e32 v40, 0x3dd53b95, v40
	v_pk_mul_f32 v[38:39], v[38:39], v[40:41] op_sel_hi:[1,0]
	v_pk_mul_f32 v[36:37], v[36:37], v[40:41] op_sel_hi:[1,0]
	v_pk_mul_f32 v[34:35], v[34:35], v[40:41] op_sel_hi:[1,0]
	v_pk_mul_f32 v[32:33], v[32:33], v[40:41] op_sel_hi:[1,0]
	s_cbranch_vccnz .LBB0_567
	v_lshl_add_u64 v[40:41], v[106:107], 0, v[56:57]
	v_lshl_add_u64 v[44:45], v[96:97], 0, v[56:57]
	global_load_dwordx4 v[40:43], v[40:41], off
	s_nop 0
	global_load_dwordx4 v[44:47], v[44:45], off
	s_waitcnt vmcnt(0)
	v_pk_mul_f32 v[50:51], v[36:37], v[40:41]
	v_pk_mul_f32 v[48:49], v[36:37], v[44:45] op_sel:[1,0] op_sel_hi:[0,0]
	v_pk_fma_f32 v[36:37], v[36:37], v[40:41], v[48:49] op_sel_hi:[1,0,1]
	v_mov_b32_e32 v44, v41
	v_mul_f32_e32 v36, v39, v45
	v_pk_fma_f32 v[52:53], v[38:39], v[44:45], v[36:37] op_sel_hi:[1,1,0] neg_lo:[0,0,1] neg_hi:[0,0,1]
	v_mov_b32_e32 v40, v45
	v_mul_f32_e32 v36, v39, v41
	v_pk_fma_f32 v[40:41], v[38:39], v[40:41], v[36:37] op_sel_hi:[1,1,0]
	v_pk_mul_f32 v[38:39], v[32:33], v[46:47] op_sel:[1,0] op_sel_hi:[0,0]
	v_pk_mul_f32 v[44:45], v[32:33], v[42:43]
	v_pk_fma_f32 v[32:33], v[32:33], v[42:43], v[38:39] op_sel_hi:[1,0,1]
	v_mov_b32_e32 v46, v43
	v_mul_f32_e32 v32, v35, v47
	v_pk_fma_f32 v[54:55], v[34:35], v[46:47], v[32:33] op_sel_hi:[1,1,0] neg_lo:[0,0,1] neg_hi:[0,0,1]
	v_mov_b32_e32 v42, v47
	v_mul_f32_e32 v32, v35, v43
	v_pk_fma_f32 v[42:43], v[34:35], v[42:43], v[32:33] op_sel_hi:[1,1,0]
	v_sub_f32_e32 v36, v50, v48
	v_sub_f32_e32 v32, v44, v38
	v_mov_b32_e32 v38, v52
	v_mov_b32_e32 v39, v40
	v_mov_b32_e32 v34, v54
	v_mov_b32_e32 v35, v42
; #define GAS __attribute__((address_space(1)))
; __device__ __forceinline__ unsigned cvt_pk_bf16(float lo, float hi) { unsigned r; asm volatile("v_cvt_pk_bf16_f32 %0, %1, %2" : "=v"(r) : "v"(lo), "v"(hi)); return r; }
;     __device__ __forceinline__ void operator()(const f32x4 (&acc)[2][2][4][2], const Unit& u, int wr, int wc, int fr, int fq) const {
;     ...
;             const int cb = u.pn * BM + bj * HALF + wc * 32, d = cb % 192; const bool rope = d >= 128; const int j0 = ((d - 128) >> 1) + 4 * fq;
; #pragma unroll
;             for (int ai = 0; ai < 2; ++ai)
; #pragma unroll
;                 for (int m = 0; m < 4; ++m) { const int r = row0 + ai * HALF + m * 16; const float s = *(const GAS float*)(rs + r) * 0.10411754831265403f;
;                     f32x4 v0 = acc[ai][bj][m][0] * s, v1 = acc[ai][bj][m][1] * s;
;                     if (rope) { const f32x4 c4 = *(const GAS f32x4*)(cs + (size_t)r * 32 + j0), s4 = *(const GAS f32x4*)(sn + (size_t)r * 32 + j0);
;                         f32x4 a, b; a[0] = v0[0] * c4[0] - v0[1] * s4[0]; a[1] = v0[0] * s4[0] + v0[1] * c4[0]; a[2] = v0[2] * c4[1] - v0[3] * s4[1]; a[3] = v0[2] * s4[1] + v0[3] * c4[1];
;                         b[0] = v1[0] * c4[2] - v1[1] * s4[2]; b[1] = v1[0] * s4[2] + v1[1] * c4[2]; b[2] = v1[2] * c4[3] - v1[3] * s4[3]; b[3] = v1[2] * s4[3] + v1[3] * c4[3]; v0 = a; v1 = b; }
;                     u32x4 w; w.x = cvt_pk_bf16(v0[0], v0[1]); w.y = cvt_pk_bf16(v0[2], v0[3]); w.z = cvt_pk_bf16(v1[0], v1[1]); w.w = cvt_pk_bf16(v1[2], v1[3]);
;                     *(GAS u32x4*)(O + (size_t)r * QW + col0 + bj * HALF) = w; }
.LBB0_567:
	v_cvt_pk_bf16_f32 v36, v36, v37
	v_cvt_pk_bf16_f32 v37, v38, v39
	v_cvt_pk_bf16_f32 v38, v32, v33
	v_cvt_pk_bf16_f32 v39, v34, v35
	global_store_dwordx4 v[100:101], v[36:39], off offset:256
	s_nop 3
	v_mov_b32_e32 v32, v196
	s_and_b64 vcc, exec, s[38:39]
	v_mul_f32_e32 v32, 0x3dd53b95, v32
	v_pk_mul_f32 v[30:31], v[30:31], v[32:33] op_sel_hi:[1,0]
	v_pk_mul_f32 v[28:29], v[28:29], v[32:33] op_sel_hi:[1,0]
	v_pk_mul_f32 v[26:27], v[26:27], v[32:33] op_sel_hi:[1,0]
	v_pk_mul_f32 v[24:25], v[24:25], v[32:33] op_sel_hi:[1,0]
	s_cbranch_vccnz .LBB0_569
	v_lshl_add_u64 v[32:33], v[98:99], 0, v[56:57]
	v_lshl_add_u64 v[36:37], v[88:89], 0, v[56:57]
	global_load_dwordx4 v[32:35], v[32:33], off
	s_nop 0
	global_load_dwordx4 v[36:39], v[36:37], off
	s_waitcnt vmcnt(0)
	v_pk_mul_f32 v[42:43], v[28:29], v[32:33]
	v_pk_mul_f32 v[40:41], v[28:29], v[36:37] op_sel:[1,0] op_sel_hi:[0,0]
	v_pk_fma_f32 v[28:29], v[28:29], v[32:33], v[40:41] op_sel_hi:[1,0,1]
	v_mov_b32_e32 v36, v33
	v_mul_f32_e32 v28, v31, v37
	v_pk_fma_f32 v[44:45], v[30:31], v[36:37], v[28:29] op_sel_hi:[1,1,0] neg_lo:[0,0,1] neg_hi:[0,0,1]
	v_mov_b32_e32 v32, v37
	v_mul_f32_e32 v28, v31, v33
	v_pk_fma_f32 v[32:33], v[30:31], v[32:33], v[28:29] op_sel_hi:[1,1,0]
	v_pk_mul_f32 v[30:31], v[24:25], v[38:39] op_sel:[1,0] op_sel_hi:[0,0]
	v_pk_mul_f32 v[36:37], v[24:25], v[34:35]
	v_pk_fma_f32 v[24:25], v[24:25], v[34:35], v[30:31] op_sel_hi:[1,0,1]
	v_mov_b32_e32 v38, v35
	v_mul_f32_e32 v24, v27, v39
	v_pk_fma_f32 v[46:47], v[26:27], v[38:39], v[24:25] op_sel_hi:[1,1,0] neg_lo:[0,0,1] neg_hi:[0,0,1]
	v_mov_b32_e32 v34, v39
	v_mul_f32_e32 v24, v27, v35
	v_pk_fma_f32 v[34:35], v[26:27], v[34:35], v[24:25] op_sel_hi:[1,1,0]
	v_sub_f32_e32 v28, v42, v40
	v_sub_f32_e32 v24, v36, v30
	v_mov_b32_e32 v30, v44
	v_mov_b32_e32 v31, v32
	v_mov_b32_e32 v26, v46
	v_mov_b32_e32 v27, v34
.LBB0_569:
	v_cvt_pk_bf16_f32 v28, v28, v29
	v_cvt_pk_bf16_f32 v29, v30, v31
	v_cvt_pk_bf16_f32 v30, v24, v25
	v_cvt_pk_bf16_f32 v31, v26, v27
	global_store_dwordx4 v[92:93], v[28:31], off offset:256
	s_nop 3
	v_mov_b32_e32 v24, v197
	s_and_b64 vcc, exec, s[38:39]
	v_mul_f32_e32 v24, 0x3dd53b95, v24
	v_pk_mul_f32 v[22:23], v[22:23], v[24:25] op_sel_hi:[1,0]
	v_pk_mul_f32 v[20:21], v[20:21], v[24:25] op_sel_hi:[1,0]
	v_pk_mul_f32 v[18:19], v[18:19], v[24:25] op_sel_hi:[1,0]
	v_pk_mul_f32 v[16:17], v[16:17], v[24:25] op_sel_hi:[1,0]
	s_cbranch_vccnz .LBB0_571
	v_lshl_add_u64 v[24:25], v[90:91], 0, v[56:57]
	v_lshl_add_u64 v[28:29], v[80:81], 0, v[56:57]
	global_load_dwordx4 v[24:27], v[24:25], off
	s_nop 0
	global_load_dwordx4 v[28:31], v[28:29], off
	s_waitcnt vmcnt(0)
	v_pk_mul_f32 v[34:35], v[20:21], v[24:25]
	v_pk_mul_f32 v[32:33], v[20:21], v[28:29] op_sel:[1,0] op_sel_hi:[0,0]
	v_pk_fma_f32 v[20:21], v[20:21], v[24:25], v[32:33] op_sel_hi:[1,0,1]
	v_mov_b32_e32 v28, v25
	v_mul_f32_e32 v20, v23, v29
	v_pk_fma_f32 v[36:37], v[22:23], v[28:29], v[20:21] op_sel_hi:[1,1,0] neg_lo:[0,0,1] neg_hi:[0,0,1]
	v_mov_b32_e32 v24, v29
	v_mul_f32_e32 v20, v23, v25
	v_pk_fma_f32 v[24:25], v[22:23], v[24:25], v[20:21] op_sel_hi:[1,1,0]
	v_pk_mul_f32 v[22:23], v[16:17], v[30:31] op_sel:[1,0] op_sel_hi:[0,0]
	v_pk_mul_f32 v[28:29], v[16:17], v[26:27]
	v_pk_fma_f32 v[16:17], v[16:17], v[26:27], v[22:23] op_sel_hi:[1,0,1]
	v_mov_b32_e32 v30, v27
	v_mul_f32_e32 v16, v19, v31
	v_pk_fma_f32 v[38:39], v[18:19], v[30:31], v[16:17] op_sel_hi:[1,1,0] neg_lo:[0,0,1] neg_hi:[0,0,1]
	v_mov_b32_e32 v26, v31
	v_mul_f32_e32 v16, v19, v27
	v_pk_fma_f32 v[26:27], v[18:19], v[26:27], v[16:17] op_sel_hi:[1,1,0]
	v_sub_f32_e32 v20, v34, v32
	v_sub_f32_e32 v16, v28, v22
	v_mov_b32_e32 v22, v36
	v_mov_b32_e32 v23, v24
	v_mov_b32_e32 v18, v38
	v_mov_b32_e32 v19, v26
; #define GAS __attribute__((address_space(1)))
; __device__ __forceinline__ unsigned cvt_pk_bf16(float lo, float hi) { unsigned r; asm volatile("v_cvt_pk_bf16_f32 %0, %1, %2" : "=v"(r) : "v"(lo), "v"(hi)); return r; }
;     __device__ __forceinline__ void operator()(const f32x4 (&acc)[2][2][4][2], const Unit& u, int wr, int wc, int fr, int fq) const {
;     ...
;             const int cb = u.pn * BM + bj * HALF + wc * 32, d = cb % 192; const bool rope = d >= 128; const int j0 = ((d - 128) >> 1) + 4 * fq;
; #pragma unroll
;             for (int ai = 0; ai < 2; ++ai)
; #pragma unroll
;                 for (int m = 0; m < 4; ++m) { const int r = row0 + ai * HALF + m * 16; const float s = *(const GAS float*)(rs + r) * 0.10411754831265403f;
;                     f32x4 v0 = acc[ai][bj][m][0] * s, v1 = acc[ai][bj][m][1] * s;
;                     if (rope) { const f32x4 c4 = *(const GAS f32x4*)(cs + (size_t)r * 32 + j0), s4 = *(const GAS f32x4*)(sn + (size_t)r * 32 + j0);
;                         f32x4 a, b; a[0] = v0[0] * c4[0] - v0[1] * s4[0]; a[1] = v0[0] * s4[0] + v0[1] * c4[0]; a[2] = v0[2] * c4[1] - v0[3] * s4[1]; a[3] = v0[2] * s4[1] + v0[3] * c4[1];
;                         b[0] = v1[0] * c4[2] - v1[1] * s4[2]; b[1] = v1[0] * s4[2] + v1[1] * c4[2]; b[2] = v1[2] * c4[3] - v1[3] * s4[3]; b[3] = v1[2] * s4[3] + v1[3] * c4[3]; v0 = a; v1 = b; }
;                     u32x4 w; w.x = cvt_pk_bf16(v0[0], v0[1]); w.y = cvt_pk_bf16(v0[2], v0[3]); w.z = cvt_pk_bf16(v1[0], v1[1]); w.w = cvt_pk_bf16(v1[2], v1[3]);
;                     *(GAS u32x4*)(O + (size_t)r * QW + col0 + bj * HALF) = w; }
.LBB0_571:
	v_cvt_pk_bf16_f32 v20, v20, v21
	v_cvt_pk_bf16_f32 v21, v22, v23
	v_cvt_pk_bf16_f32 v22, v16, v17
	v_cvt_pk_bf16_f32 v23, v18, v19
	global_store_dwordx4 v[84:85], v[20:23], off offset:256
	s_nop 3
	v_mov_b32_e32 v16, v198
	s_and_b64 vcc, exec, s[38:39]
	v_mul_f32_e32 v16, 0x3dd53b95, v16
	v_pk_mul_f32 v[14:15], v[14:15], v[16:17] op_sel_hi:[1,0]
	v_pk_mul_f32 v[12:13], v[12:13], v[16:17] op_sel_hi:[1,0]
	v_pk_mul_f32 v[10:11], v[10:11], v[16:17] op_sel_hi:[1,0]
	v_pk_mul_f32 v[8:9], v[8:9], v[16:17] op_sel_hi:[1,0]
	s_cbranch_vccnz .LBB0_573
	v_lshl_add_u64 v[16:17], v[82:83], 0, v[56:57]
	v_lshl_add_u64 v[20:21], v[72:73], 0, v[56:57]
	global_load_dwordx4 v[16:19], v[16:17], off
	s_nop 0
	global_load_dwordx4 v[20:23], v[20:21], off
	s_waitcnt vmcnt(0)
	v_pk_mul_f32 v[26:27], v[12:13], v[16:17]
	v_pk_mul_f32 v[24:25], v[12:13], v[20:21] op_sel:[1,0] op_sel_hi:[0,0]
	v_pk_fma_f32 v[12:13], v[12:13], v[16:17], v[24:25] op_sel_hi:[1,0,1]
	v_mov_b32_e32 v20, v17
	v_mul_f32_e32 v12, v15, v21
	v_pk_fma_f32 v[28:29], v[14:15], v[20:21], v[12:13] op_sel_hi:[1,1,0] neg_lo:[0,0,1] neg_hi:[0,0,1]
	v_mov_b32_e32 v16, v21
	v_mul_f32_e32 v12, v15, v17
	v_pk_fma_f32 v[16:17], v[14:15], v[16:17], v[12:13] op_sel_hi:[1,1,0]
	v_pk_mul_f32 v[14:15], v[8:9], v[22:23] op_sel:[1,0] op_sel_hi:[0,0]
	v_pk_mul_f32 v[20:21], v[8:9], v[18:19]
	v_pk_fma_f32 v[8:9], v[8:9], v[18:19], v[14:15] op_sel_hi:[1,0,1]
	v_mov_b32_e32 v22, v19
	v_mul_f32_e32 v8, v11, v23
	v_pk_fma_f32 v[30:31], v[10:11], v[22:23], v[8:9] op_sel_hi:[1,1,0] neg_lo:[0,0,1] neg_hi:[0,0,1]
	v_mov_b32_e32 v18, v23
	v_mul_f32_e32 v8, v11, v19
	v_pk_fma_f32 v[18:19], v[10:11], v[18:19], v[8:9] op_sel_hi:[1,1,0]
	v_sub_f32_e32 v12, v26, v24
	v_sub_f32_e32 v8, v20, v14
	v_mov_b32_e32 v14, v28
	v_mov_b32_e32 v15, v16
	v_mov_b32_e32 v10, v30
	v_mov_b32_e32 v11, v18
.LBB0_573:
	v_cvt_pk_bf16_f32 v12, v12, v13
	v_cvt_pk_bf16_f32 v13, v14, v15
	v_cvt_pk_bf16_f32 v14, v8, v9
	v_cvt_pk_bf16_f32 v15, v10, v11
	global_store_dwordx4 v[76:77], v[12:15], off offset:256
	s_nop 3
	v_mov_b32_e32 v8, v199
	s_and_b64 vcc, exec, s[38:39]
	v_mul_f32_e32 v8, 0x3dd53b95, v8
	v_pk_mul_f32 v[6:7], v[6:7], v[8:9] op_sel_hi:[1,0]
	v_pk_mul_f32 v[4:5], v[4:5], v[8:9] op_sel_hi:[1,0]
	v_pk_mul_f32 v[2:3], v[2:3], v[8:9] op_sel_hi:[1,0]
	v_pk_mul_f32 v[0:1], v[0:1], v[8:9] op_sel_hi:[1,0]
	s_cbranch_vccnz .LBB0_575
	v_lshl_add_u64 v[8:9], v[74:75], 0, v[56:57]
	v_lshl_add_u64 v[12:13], v[64:65], 0, v[56:57]
	global_load_dwordx4 v[8:11], v[8:9], off
	s_nop 0
	global_load_dwordx4 v[12:15], v[12:13], off
	s_waitcnt vmcnt(0)
	v_pk_mul_f32 v[18:19], v[4:5], v[8:9]
	v_pk_mul_f32 v[16:17], v[4:5], v[12:13] op_sel:[1,0] op_sel_hi:[0,0]
	v_pk_fma_f32 v[4:5], v[4:5], v[8:9], v[16:17] op_sel_hi:[1,0,1]
	v_mov_b32_e32 v12, v9
	v_mul_f32_e32 v4, v7, v13
	v_pk_fma_f32 v[20:21], v[6:7], v[12:13], v[4:5] op_sel_hi:[1,1,0] neg_lo:[0,0,1] neg_hi:[0,0,1]
	v_mov_b32_e32 v8, v13
	v_mul_f32_e32 v4, v7, v9
	v_pk_fma_f32 v[8:9], v[6:7], v[8:9], v[4:5] op_sel_hi:[1,1,0]
	v_pk_mul_f32 v[6:7], v[0:1], v[14:15] op_sel:[1,0] op_sel_hi:[0,0]
	v_pk_mul_f32 v[12:13], v[0:1], v[10:11]
	v_pk_fma_f32 v[0:1], v[0:1], v[10:11], v[6:7] op_sel_hi:[1,0,1]
	v_mov_b32_e32 v14, v11
	v_mul_f32_e32 v0, v3, v15
	v_pk_fma_f32 v[22:23], v[2:3], v[14:15], v[0:1] op_sel_hi:[1,1,0] neg_lo:[0,0,1] neg_hi:[0,0,1]
	v_mov_b32_e32 v10, v15
	v_mul_f32_e32 v0, v3, v11
	v_pk_fma_f32 v[10:11], v[2:3], v[10:11], v[0:1] op_sel_hi:[1,1,0]
	v_sub_f32_e32 v4, v18, v16
	v_sub_f32_e32 v0, v12, v6
	v_mov_b32_e32 v6, v20
	v_mov_b32_e32 v7, v8
	v_mov_b32_e32 v2, v22
	v_mov_b32_e32 v3, v10
.LBB0_575:
	s_and_b64 vcc, exec, s[36:37]
	s_mov_b64 s[36:37], -1
	v_cvt_pk_bf16_f32 v4, v4, v5
	v_cvt_pk_bf16_f32 v5, v6, v7
	v_cvt_pk_bf16_f32 v6, v0, v1
	v_cvt_pk_bf16_f32 v7, v2, v3
	global_store_dwordx4 v[66:67], v[4:7], off offset:256
	s_nop 3
	s_cbranch_vccnz .LBB0_533
	s_andn2_b64 vcc, exec, s[14:15]
	v_mov_b32 v0, 0
	s_cbranch_vccnz .LBB0_532
	s_barrier
	s_branch .LBB0_532

; #define GAS __attribute__((address_space(1)))
; __device__ __forceinline__ unsigned cvt_pk_bf16(float lo, float hi) { unsigned r; asm volatile("v_cvt_pk_bf16_f32 %0, %1, %2" : "=v"(r) : "v"(lo), "v"(hi)); return r; }
;     __device__ __forceinline__ void operator()(const f32x4 (&acc)[2][2][4][2], const Unit& u, int wr, int wc, int fr, int fq) const {
;         const int row0 = u.pm * BM + wr * 64 + fr, col0 = u.pn * BM + wc * 32 + 8 * fq;
; #pragma unroll
;         for (int ai = 0; ai < 2; ++ai)
; #pragma unroll
;             for (int m = 0; m < 4; ++m) { const int r = row0 + ai * HALF + m * 16; float s = rs ? *(const GAS float*)(rs + r) : 1.f; if (ssqp) s = rsqrtf((float)*(const GAS u64_t*)(ssqp + r) * (SSQ_INV / DM) + EPS); bf16_t* rowp = O + (size_t)r * ldc + col0;
; #pragma unroll
;                 for (int bj = 0; bj < 2; ++bj) { const f32x4 v0 = acc[ai][bj][m][0] * s, v1 = acc[ai][bj][m][1] * s;
;                     u32x4 w; w.x = cvt_pk_bf16(v0[0], v0[1]); w.y = cvt_pk_bf16(v0[2], v0[3]); w.z = cvt_pk_bf16(v1[0], v1[1]); w.w = cvt_pk_bf16(v1[2], v1[3]);
;                     *(GAS u32x4*)(rowp + bj * HALF) = w; } }
.LBB0_601:
	v_lshl_add_u32 v144, s60, 8, v146
	v_ashrrev_i32_e32 v145, 31, v144
	v_lshl_add_u64 v[140:141], v[144:145], 2, s[16:17]
	global_load_dword v150, v[140:141], off
	global_load_dword v154, v[140:141], off offset:64
	global_load_dword v156, v[140:141], off offset:128
	global_load_dword v158, v[140:141], off offset:192
	global_load_dword v160, v[140:141], off offset:512
	global_load_dword v162, v[140:141], off offset:576
	global_load_dword v164, v[140:141], off offset:640
	global_load_dword v166, v[140:141], off offset:704
	v_lshl_or_b32 v138, s59, 8, v148
	v_ashrrev_i32_e32 v139, 31, v138
	v_lshlrev_b64 v[142:143], 12, v[144:145]
	v_lshl_add_u64 v[152:153], s[40:41], 0, v[142:143]
	v_lshlrev_b64 v[142:143], 1, v[138:139]
	v_lshl_add_u64 v[138:139], v[152:153], 0, v[142:143]
	s_mov_b64 s[38:39], 0x80000
	s_waitcnt vmcnt(0)
	v_pk_mul_f32 v[126:127], v[126:127], v[150:151] op_sel_hi:[1,0]
	v_pk_mul_f32 v[124:125], v[124:125], v[150:151] op_sel_hi:[1,0]
	v_pk_mul_f32 v[152:153], v[122:123], v[150:151] op_sel_hi:[1,0]
	v_pk_mul_f32 v[122:123], v[120:121], v[150:151] op_sel_hi:[1,0]
	v_cvt_pk_bf16_f32 v120, v124, v125
	v_cvt_pk_bf16_f32 v121, v126, v127
	v_pk_mul_f32 v[116:117], v[116:117], v[150:151] op_sel_hi:[1,0]
	v_cvt_pk_bf16_f32 v122, v122, v123
	v_cvt_pk_bf16_f32 v123, v152, v153
	global_store_dwordx4 v[138:139], v[120:123], off
	s_nop 3
	v_pk_mul_f32 v[118:119], v[118:119], v[150:151] op_sel_hi:[1,0]
	s_nop 0
	v_pk_mul_f32 v[120:121], v[114:115], v[150:151] op_sel_hi:[1,0]
	v_pk_mul_f32 v[114:115], v[112:113], v[150:151] op_sel_hi:[1,0]
	v_cvt_pk_bf16_f32 v112, v116, v117
	v_cvt_pk_bf16_f32 v113, v118, v119
	s_nop 0
	v_cvt_pk_bf16_f32 v114, v114, v115
	v_cvt_pk_bf16_f32 v115, v120, v121
	global_store_dwordx4 v[138:139], v[112:115], off offset:256
	s_nop 3
	s_nop 1
	v_or_b32_e32 v112, 16, v144
	v_ashrrev_i32_e32 v113, 31, v112
	v_lshl_add_u64 v[114:115], v[112:113], 2, s[16:17]
	v_mov_b32_e32 v114, v154
	v_lshlrev_b64 v[112:113], 12, v[112:113]
	v_lshl_add_u64 v[112:113], s[40:41], 0, v[112:113]
	v_lshl_add_u64 v[112:113], v[112:113], 0, v[142:143]
	v_pk_mul_f32 v[110:111], v[110:111], v[114:115] op_sel_hi:[1,0]
	v_pk_mul_f32 v[108:109], v[108:109], v[114:115] op_sel_hi:[1,0]
	v_pk_mul_f32 v[116:117], v[106:107], v[114:115] op_sel_hi:[1,0]
	v_pk_mul_f32 v[106:107], v[104:105], v[114:115] op_sel_hi:[1,0]
	v_cvt_pk_bf16_f32 v104, v108, v109
	v_cvt_pk_bf16_f32 v105, v110, v111
	v_pk_mul_f32 v[100:101], v[100:101], v[114:115] op_sel_hi:[1,0]
	v_cvt_pk_bf16_f32 v106, v106, v107
	v_cvt_pk_bf16_f32 v107, v116, v117
	global_store_dwordx4 v[112:113], v[104:107], off
	s_nop 3
	v_pk_mul_f32 v[102:103], v[102:103], v[114:115] op_sel_hi:[1,0]
	s_nop 0
	v_pk_mul_f32 v[104:105], v[98:99], v[114:115] op_sel_hi:[1,0]
	v_pk_mul_f32 v[98:99], v[96:97], v[114:115] op_sel_hi:[1,0]
	v_cvt_pk_bf16_f32 v96, v100, v101
	v_cvt_pk_bf16_f32 v97, v102, v103
	s_nop 0
	v_cvt_pk_bf16_f32 v98, v98, v99
	v_cvt_pk_bf16_f32 v99, v104, v105
	global_store_dwordx4 v[112:113], v[96:99], off offset:256
	s_nop 3
	s_nop 1
	v_or_b32_e32 v96, 32, v144
	v_ashrrev_i32_e32 v97, 31, v96
	v_lshl_add_u64 v[98:99], v[96:97], 2, s[16:17]
	v_mov_b32_e32 v98, v156
	v_lshlrev_b64 v[96:97], 12, v[96:97]
	v_lshl_add_u64 v[96:97], s[40:41], 0, v[96:97]
	v_lshl_add_u64 v[96:97], v[96:97], 0, v[142:143]
	v_pk_mul_f32 v[94:95], v[94:95], v[98:99] op_sel_hi:[1,0]
	v_pk_mul_f32 v[92:93], v[92:93], v[98:99] op_sel_hi:[1,0]
	v_pk_mul_f32 v[100:101], v[90:91], v[98:99] op_sel_hi:[1,0]
	v_pk_mul_f32 v[90:91], v[88:89], v[98:99] op_sel_hi:[1,0]
	v_cvt_pk_bf16_f32 v88, v92, v93
	v_cvt_pk_bf16_f32 v89, v94, v95
	v_pk_mul_f32 v[84:85], v[84:85], v[98:99] op_sel_hi:[1,0]
	v_cvt_pk_bf16_f32 v90, v90, v91
	v_cvt_pk_bf16_f32 v91, v100, v101
	global_store_dwordx4 v[96:97], v[88:91], off
	s_nop 3
	v_pk_mul_f32 v[86:87], v[86:87], v[98:99] op_sel_hi:[1,0]
	s_nop 0
	v_pk_mul_f32 v[88:89], v[82:83], v[98:99] op_sel_hi:[1,0]
	v_pk_mul_f32 v[82:83], v[80:81], v[98:99] op_sel_hi:[1,0]
	v_cvt_pk_bf16_f32 v80, v84, v85
	v_cvt_pk_bf16_f32 v81, v86, v87
	s_nop 0
	v_cvt_pk_bf16_f32 v82, v82, v83
	v_cvt_pk_bf16_f32 v83, v88, v89
	global_store_dwordx4 v[96:97], v[80:83], off offset:256
	s_nop 3
	s_nop 1
	v_or_b32_e32 v80, 48, v144
	v_ashrrev_i32_e32 v81, 31, v80
	v_lshl_add_u64 v[82:83], v[80:81], 2, s[16:17]
	v_mov_b32_e32 v82, v158
	v_lshlrev_b64 v[80:81], 12, v[80:81]
	v_lshl_add_u64 v[80:81], s[40:41], 0, v[80:81]
	v_lshl_add_u64 v[80:81], v[80:81], 0, v[142:143]
	v_pk_mul_f32 v[78:79], v[78:79], v[82:83] op_sel_hi:[1,0]
	v_pk_mul_f32 v[76:77], v[76:77], v[82:83] op_sel_hi:[1,0]
	v_pk_mul_f32 v[84:85], v[74:75], v[82:83] op_sel_hi:[1,0]
	v_pk_mul_f32 v[74:75], v[72:73], v[82:83] op_sel_hi:[1,0]
	v_cvt_pk_bf16_f32 v72, v76, v77
	v_cvt_pk_bf16_f32 v73, v78, v79
	v_pk_mul_f32 v[70:71], v[70:71], v[82:83] op_sel_hi:[1,0]
	v_cvt_pk_bf16_f32 v74, v74, v75
	v_cvt_pk_bf16_f32 v75, v84, v85
; #define GAS __attribute__((address_space(1)))
; __device__ __forceinline__ unsigned cvt_pk_bf16(float lo, float hi) { unsigned r; asm volatile("v_cvt_pk_bf16_f32 %0, %1, %2" : "=v"(r) : "v"(lo), "v"(hi)); return r; }
;     __device__ __forceinline__ void operator()(const f32x4 (&acc)[2][2][4][2], const Unit& u, int wr, int wc, int fr, int fq) const {
;         const int row0 = u.pm * BM + wr * 64 + fr, col0 = u.pn * BM + wc * 32 + 8 * fq;
; #pragma unroll
;         for (int ai = 0; ai < 2; ++ai)
; #pragma unroll
;             for (int m = 0; m < 4; ++m) { const int r = row0 + ai * HALF + m * 16; float s = rs ? *(const GAS float*)(rs + r) : 1.f; if (ssqp) s = rsqrtf((float)*(const GAS u64_t*)(ssqp + r) * (SSQ_INV / DM) + EPS); bf16_t* rowp = O + (size_t)r * ldc + col0;
; #pragma unroll
;                 for (int bj = 0; bj < 2; ++bj) { const f32x4 v0 = acc[ai][bj][m][0] * s, v1 = acc[ai][bj][m][1] * s;
;                     u32x4 w; w.x = cvt_pk_bf16(v0[0], v0[1]); w.y = cvt_pk_bf16(v0[2], v0[3]); w.z = cvt_pk_bf16(v1[0], v1[1]); w.w = cvt_pk_bf16(v1[2], v1[3]);
;                     *(GAS u32x4*)(rowp + bj * HALF) = w; } }
	global_store_dwordx4 v[80:81], v[72:75], off
	s_nop 3
	v_pk_mul_f32 v[68:69], v[68:69], v[82:83] op_sel_hi:[1,0]
	s_nop 0
	v_pk_mul_f32 v[72:73], v[66:67], v[82:83] op_sel_hi:[1,0]
	v_pk_mul_f32 v[66:67], v[64:65], v[82:83] op_sel_hi:[1,0]
	v_cvt_pk_bf16_f32 v64, v68, v69
	v_cvt_pk_bf16_f32 v65, v70, v71
	s_nop 0
	v_cvt_pk_bf16_f32 v66, v66, v67
	v_cvt_pk_bf16_f32 v67, v72, v73
	global_store_dwordx4 v[80:81], v[64:67], off offset:256
	s_nop 3
	s_nop 1
	v_mov_b32_e32 v64, v160
	v_pk_mul_f32 v[60:61], v[60:61], v[64:65] op_sel_hi:[1,0]
	v_lshl_add_u64 v[66:67], v[138:139], 0, s[38:39]
	s_mov_b32 s38, 0x80000
	v_pk_mul_f32 v[68:69], v[58:59], v[64:65] op_sel_hi:[1,0]
	v_pk_mul_f32 v[58:59], v[56:57], v[64:65] op_sel_hi:[1,0]
	v_cvt_pk_bf16_f32 v56, v60, v61
	v_add_co_u32_e32 v60, vcc, s38, v138
	v_pk_mul_f32 v[62:63], v[62:63], v[64:65] op_sel_hi:[1,0]
	s_nop 0
	v_addc_co_u32_e32 v61, vcc, 0, v139, vcc
	v_cvt_pk_bf16_f32 v57, v62, v63
	v_cvt_pk_bf16_f32 v58, v58, v59
	v_cvt_pk_bf16_f32 v59, v68, v69
	global_store_dwordx4 v[60:61], v[56:59], off
	s_nop 3
	v_pk_mul_f32 v[54:55], v[54:55], v[64:65] op_sel_hi:[1,0]
	v_pk_mul_f32 v[52:53], v[52:53], v[64:65] op_sel_hi:[1,0]
	v_pk_mul_f32 v[56:57], v[50:51], v[64:65] op_sel_hi:[1,0]
	v_pk_mul_f32 v[50:51], v[48:49], v[64:65] op_sel_hi:[1,0]
	v_cvt_pk_bf16_f32 v48, v52, v53
	v_cvt_pk_bf16_f32 v49, v54, v55
	s_mov_b64 s[38:39], 0x90000
	v_cvt_pk_bf16_f32 v50, v50, v51
	v_cvt_pk_bf16_f32 v51, v56, v57
	global_store_dwordx4 v[66:67], v[48:51], off offset:256
	s_nop 3
	s_nop 1
	v_mov_b32_e32 v48, v162
	v_pk_mul_f32 v[44:45], v[44:45], v[48:49] op_sel_hi:[1,0]
	v_lshl_add_u64 v[50:51], v[138:139], 0, s[38:39]
	s_mov_b32 s38, 0x90000
	v_pk_mul_f32 v[52:53], v[42:43], v[48:49] op_sel_hi:[1,0]
	v_pk_mul_f32 v[42:43], v[40:41], v[48:49] op_sel_hi:[1,0]
	v_cvt_pk_bf16_f32 v40, v44, v45
	v_add_co_u32_e32 v44, vcc, s38, v138
	v_pk_mul_f32 v[46:47], v[46:47], v[48:49] op_sel_hi:[1,0]
	s_nop 0
	v_addc_co_u32_e32 v45, vcc, 0, v139, vcc
	v_cvt_pk_bf16_f32 v41, v46, v47
	v_cvt_pk_bf16_f32 v42, v42, v43
	v_cvt_pk_bf16_f32 v43, v52, v53
	global_store_dwordx4 v[44:45], v[40:43], off
	s_nop 3
	v_pk_mul_f32 v[38:39], v[38:39], v[48:49] op_sel_hi:[1,0]
	v_pk_mul_f32 v[36:37], v[36:37], v[48:49] op_sel_hi:[1,0]
	v_pk_mul_f32 v[40:41], v[34:35], v[48:49] op_sel_hi:[1,0]
	v_pk_mul_f32 v[34:35], v[32:33], v[48:49] op_sel_hi:[1,0]
	v_cvt_pk_bf16_f32 v32, v36, v37
	v_cvt_pk_bf16_f32 v33, v38, v39
	s_mov_b64 s[38:39], 0xa0000
	v_cvt_pk_bf16_f32 v34, v34, v35
	v_cvt_pk_bf16_f32 v35, v40, v41
	global_store_dwordx4 v[50:51], v[32:35], off offset:256
	s_nop 3
	s_nop 1
	v_mov_b32_e32 v32, v164
	v_pk_mul_f32 v[28:29], v[28:29], v[32:33] op_sel_hi:[1,0]
	v_lshl_add_u64 v[34:35], v[138:139], 0, s[38:39]
	s_mov_b32 s38, 0xa0000
	v_pk_mul_f32 v[36:37], v[26:27], v[32:33] op_sel_hi:[1,0]
	v_pk_mul_f32 v[26:27], v[24:25], v[32:33] op_sel_hi:[1,0]
	v_cvt_pk_bf16_f32 v24, v28, v29
	v_add_co_u32_e32 v28, vcc, s38, v138
	v_pk_mul_f32 v[30:31], v[30:31], v[32:33] op_sel_hi:[1,0]
	s_nop 0
	v_addc_co_u32_e32 v29, vcc, 0, v139, vcc
	v_cvt_pk_bf16_f32 v25, v30, v31
	v_cvt_pk_bf16_f32 v26, v26, v27
	v_cvt_pk_bf16_f32 v27, v36, v37
	global_store_dwordx4 v[28:29], v[24:27], off
	s_nop 3
	v_pk_mul_f32 v[22:23], v[22:23], v[32:33] op_sel_hi:[1,0]
	v_pk_mul_f32 v[20:21], v[20:21], v[32:33] op_sel_hi:[1,0]
	v_pk_mul_f32 v[24:25], v[18:19], v[32:33] op_sel_hi:[1,0]
	v_pk_mul_f32 v[18:19], v[16:17], v[32:33] op_sel_hi:[1,0]
	v_cvt_pk_bf16_f32 v16, v20, v21
	v_cvt_pk_bf16_f32 v17, v22, v23
	s_mov_b64 s[38:39], 0xb0000
	v_cvt_pk_bf16_f32 v18, v18, v19
	v_cvt_pk_bf16_f32 v19, v24, v25
	global_store_dwordx4 v[34:35], v[16:19], off offset:256
	s_nop 3
	s_nop 1
	v_mov_b32_e32 v16, v166
	v_pk_mul_f32 v[12:13], v[12:13], v[16:17] op_sel_hi:[1,0]
	v_lshl_add_u64 v[18:19], v[138:139], 0, s[38:39]
	s_mov_b32 s38, 0xb0000
	v_pk_mul_f32 v[20:21], v[10:11], v[16:17] op_sel_hi:[1,0]
	v_pk_mul_f32 v[10:11], v[8:9], v[16:17] op_sel_hi:[1,0]
	v_cvt_pk_bf16_f32 v8, v12, v13
	v_add_co_u32_e32 v12, vcc, s38, v138
	v_pk_mul_f32 v[14:15], v[14:15], v[16:17] op_sel_hi:[1,0]
	s_nop 0
	v_addc_co_u32_e32 v13, vcc, 0, v139, vcc
	v_cvt_pk_bf16_f32 v9, v14, v15
	v_cvt_pk_bf16_f32 v10, v10, v11
	v_cvt_pk_bf16_f32 v11, v20, v21
	global_store_dwordx4 v[12:13], v[8:11], off
	s_nop 3
	v_pk_mul_f32 v[6:7], v[6:7], v[16:17] op_sel_hi:[1,0]
	v_pk_mul_f32 v[4:5], v[4:5], v[16:17] op_sel_hi:[1,0]
	v_pk_mul_f32 v[8:9], v[2:3], v[16:17] op_sel_hi:[1,0]
	v_pk_mul_f32 v[2:3], v[0:1], v[16:17] op_sel_hi:[1,0]
	v_cvt_pk_bf16_f32 v0, v4, v5
	v_cvt_pk_bf16_f32 v1, v6, v7
	s_mov_b64 s[38:39], -1
	v_cvt_pk_bf16_f32 v2, v2, v3
	v_cvt_pk_bf16_f32 v3, v8, v9
	s_and_b64 vcc, exec, s[36:37]
	global_store_dwordx4 v[18:19], v[0:3], off offset:256
	s_nop 3
	s_cbranch_vccnz .LBB0_587
	s_andn2_b64 vcc, exec, s[14:15]
	v_mov_b32 v0, 0
	s_cbranch_vccnz .LBB0_586
	s_barrier
	s_branch .LBB0_586

; #define GAS __attribute__((address_space(1)))
; __device__ __forceinline__ unsigned cvt_pk_bf16(float lo, float hi) { unsigned r; asm volatile("v_cvt_pk_bf16_f32 %0, %1, %2" : "=v"(r) : "v"(lo), "v"(hi)); return r; }
;     __device__ __forceinline__ void operator()(const f32x4 (&acc)[2][2][4][2], const Unit& u, int wr, int wc, int fr, int fq) const {
;         const int row0 = u.pm * BM + wr * 64 + fr, col0 = u.pn * BM + wc * 32 + 8 * fq;
; #pragma unroll
;         for (int ai = 0; ai < 2; ++ai)
; #pragma unroll
;             for (int m = 0; m < 4; ++m) { const int r = row0 + ai * HALF + m * 16; float s = rs ? *(const GAS float*)(rs + r) : 1.f; if (ssqp) s = rsqrtf((float)*(const GAS u64_t*)(ssqp + r) * (SSQ_INV / DM) + EPS); bf16_t* rowp = O + (size_t)r * ldc + col0;
; #pragma unroll
;                 for (int bj = 0; bj < 2; ++bj) { const f32x4 v0 = acc[ai][bj][m][0] * s, v1 = acc[ai][bj][m][1] * s;
;                     u32x4 w; w.x = cvt_pk_bf16(v0[0], v0[1]); w.y = cvt_pk_bf16(v0[2], v0[3]); w.z = cvt_pk_bf16(v1[0], v1[1]); w.w = cvt_pk_bf16(v1[2], v1[3]);
;                     *(GAS u32x4*)(rowp + bj * HALF) = w; } }
.LBB0_647:
	v_lshl_add_u32 v138, s56, 8, v146
	v_ashrrev_i32_e32 v139, 31, v138
	v_lshl_add_u64 v[140:141], v[138:139], 3, s[80:81]
	global_load_dwordx2 v[142:143], v[140:141], off
	global_load_dwordx2 v[156:157], v[140:141], off offset:128
	global_load_dwordx2 v[158:159], v[140:141], off offset:256
	global_load_dwordx2 v[160:161], v[140:141], off offset:384
	global_load_dwordx2 v[162:163], v[140:141], off offset:1024
	global_load_dwordx2 v[164:165], v[140:141], off offset:1152
	global_load_dwordx2 v[166:167], v[140:141], off offset:1280
	global_load_dwordx2 v[168:169], v[140:141], off offset:1408
	s_mov_b32 s41, 0x800000
	v_lshl_or_b32 v144, s55, 8, v148
	v_ashrrev_i32_e32 v145, 31, v144
	s_movk_i32 s40, 0x1200
	v_lshlrev_b64 v[144:145], 1, v[144:145]
	s_waitcnt vmcnt(0)
	v_ffbh_u32_e32 v139, v143
	v_min_u32_e32 v139, 32, v139
	v_lshlrev_b64 v[142:143], v139, v[142:143]
	v_min_u32_e32 v142, 1, v142
	v_or_b32_e32 v142, v143, v142
	v_cvt_f32_u32_e32 v142, v142
	v_sub_u32_e32 v139, 32, v139
	v_ldexp_f32 v139, v142, v139
	v_fmamk_f32 v139, v139, 0x32000000, v232
	v_cmp_gt_f32_e32 vcc, s41, v139
	v_mul_f32_e32 v142, 0x4b800000, v139
	s_nop 0
	v_cndmask_b32_e32 v139, v139, v142, vcc
	v_rsq_f32_e32 v139, v139
	s_nop 0
	v_mul_f32_e32 v142, 0x45800000, v139
	v_cndmask_b32_e32 v150, v139, v142, vcc
	v_mov_b64_e32 v[142:143], s[30:31]
	v_mad_i64_i32 v[152:153], s[38:39], v138, s40, v[142:143]
	v_lshl_add_u64 v[152:153], v[152:153], 0, v[144:145]
	v_pk_mul_f32 v[126:127], v[126:127], v[150:151] op_sel_hi:[1,0]
	v_pk_mul_f32 v[124:125], v[124:125], v[150:151] op_sel_hi:[1,0]
	v_pk_mul_f32 v[154:155], v[122:123], v[150:151] op_sel_hi:[1,0]
	v_pk_mul_f32 v[122:123], v[120:121], v[150:151] op_sel_hi:[1,0]
	v_cvt_pk_bf16_f32 v120, v124, v125
	v_cvt_pk_bf16_f32 v121, v126, v127
	v_pk_mul_f32 v[116:117], v[116:117], v[150:151] op_sel_hi:[1,0]
	v_cvt_pk_bf16_f32 v122, v122, v123
	v_cvt_pk_bf16_f32 v123, v154, v155
	global_store_dwordx4 v[152:153], v[120:123], off
	s_nop 3
	v_pk_mul_f32 v[118:119], v[118:119], v[150:151] op_sel_hi:[1,0]
	s_nop 0
	v_pk_mul_f32 v[120:121], v[114:115], v[150:151] op_sel_hi:[1,0]
	v_pk_mul_f32 v[114:115], v[112:113], v[150:151] op_sel_hi:[1,0]
	v_cvt_pk_bf16_f32 v112, v116, v117
	v_cvt_pk_bf16_f32 v113, v118, v119
	s_nop 0
	v_cvt_pk_bf16_f32 v114, v114, v115
	v_cvt_pk_bf16_f32 v115, v120, v121
	global_store_dwordx4 v[152:153], v[112:115], off offset:256
	s_nop 3
	s_nop 1
	v_or_b32_e32 v112, 16, v138
	v_ashrrev_i32_e32 v113, 31, v112
	v_lshl_add_u64 v[114:115], v[112:113], 3, s[80:81]
	v_mov_b32_e32 v114, v156
	v_mov_b32_e32 v115, v157
	v_ffbh_u32_e32 v113, v115
	v_min_u32_e32 v113, 32, v113
	v_lshlrev_b64 v[114:115], v113, v[114:115]
	v_min_u32_e32 v114, 1, v114
	v_or_b32_e32 v114, v115, v114
	v_cvt_f32_u32_e32 v114, v114
	v_sub_u32_e32 v113, 32, v113
	v_ldexp_f32 v113, v114, v113
	v_fmamk_f32 v113, v113, 0x32000000, v232
	v_cmp_gt_f32_e32 vcc, s41, v113
	v_mul_f32_e32 v114, 0x4b800000, v113
	s_nop 0
	v_cndmask_b32_e32 v113, v113, v114, vcc
	v_rsq_f32_e32 v113, v113
	s_nop 0
	v_mul_f32_e32 v114, 0x45800000, v113
	v_cndmask_b32_e32 v114, v113, v114, vcc
	v_mad_i64_i32 v[112:113], s[38:39], v112, s40, v[142:143]
	v_lshl_add_u64 v[112:113], v[112:113], 0, v[144:145]
	v_pk_mul_f32 v[110:111], v[110:111], v[114:115] op_sel_hi:[1,0]
	v_pk_mul_f32 v[108:109], v[108:109], v[114:115] op_sel_hi:[1,0]
	v_pk_mul_f32 v[116:117], v[106:107], v[114:115] op_sel_hi:[1,0]
	v_pk_mul_f32 v[106:107], v[104:105], v[114:115] op_sel_hi:[1,0]
	v_cvt_pk_bf16_f32 v104, v108, v109
	v_cvt_pk_bf16_f32 v105, v110, v111
	v_pk_mul_f32 v[100:101], v[100:101], v[114:115] op_sel_hi:[1,0]
	v_cvt_pk_bf16_f32 v106, v106, v107
	v_cvt_pk_bf16_f32 v107, v116, v117
	global_store_dwordx4 v[112:113], v[104:107], off
	s_nop 3
	v_pk_mul_f32 v[102:103], v[102:103], v[114:115] op_sel_hi:[1,0]
	s_nop 0
	v_pk_mul_f32 v[104:105], v[98:99], v[114:115] op_sel_hi:[1,0]
	v_pk_mul_f32 v[98:99], v[96:97], v[114:115] op_sel_hi:[1,0]
	v_cvt_pk_bf16_f32 v96, v100, v101
	v_cvt_pk_bf16_f32 v97, v102, v103
	s_nop 0
	v_cvt_pk_bf16_f32 v98, v98, v99
	v_cvt_pk_bf16_f32 v99, v104, v105
	global_store_dwordx4 v[112:113], v[96:99], off offset:256
	s_nop 3
	s_nop 1
	v_or_b32_e32 v96, 32, v138
	v_ashrrev_i32_e32 v97, 31, v96
	v_lshl_add_u64 v[98:99], v[96:97], 3, s[80:81]
	v_mov_b32_e32 v98, v158
	v_mov_b32_e32 v99, v159
	v_ffbh_u32_e32 v97, v99
	v_min_u32_e32 v97, 32, v97
	v_lshlrev_b64 v[98:99], v97, v[98:99]
	v_min_u32_e32 v98, 1, v98
	v_or_b32_e32 v98, v99, v98
	v_cvt_f32_u32_e32 v98, v98
	v_sub_u32_e32 v97, 32, v97
	v_ldexp_f32 v97, v98, v97
	v_fmamk_f32 v97, v97, 0x32000000, v232
	v_cmp_gt_f32_e32 vcc, s41, v97
	v_mul_f32_e32 v98, 0x4b800000, v97
	s_nop 0
	v_cndmask_b32_e32 v97, v97, v98, vcc
	v_rsq_f32_e32 v97, v97
	s_nop 0
	v_mul_f32_e32 v98, 0x45800000, v97
	v_cndmask_b32_e32 v98, v97, v98, vcc
	v_mad_i64_i32 v[96:97], s[38:39], v96, s40, v[142:143]
	v_lshl_add_u64 v[96:97], v[96:97], 0, v[144:145]
	v_pk_mul_f32 v[94:95], v[94:95], v[98:99] op_sel_hi:[1,0]
	v_pk_mul_f32 v[92:93], v[92:93], v[98:99] op_sel_hi:[1,0]
	v_pk_mul_f32 v[100:101], v[90:91], v[98:99] op_sel_hi:[1,0]
	v_pk_mul_f32 v[90:91], v[88:89], v[98:99] op_sel_hi:[1,0]
	v_cvt_pk_bf16_f32 v88, v92, v93
	v_cvt_pk_bf16_f32 v89, v94, v95
	v_pk_mul_f32 v[84:85], v[84:85], v[98:99] op_sel_hi:[1,0]
	v_cvt_pk_bf16_f32 v90, v90, v91
	v_cvt_pk_bf16_f32 v91, v100, v101
	global_store_dwordx4 v[96:97], v[88:91], off
	s_nop 3
	v_pk_mul_f32 v[86:87], v[86:87], v[98:99] op_sel_hi:[1,0]
	s_nop 0
	v_pk_mul_f32 v[88:89], v[82:83], v[98:99] op_sel_hi:[1,0]
	v_pk_mul_f32 v[82:83], v[80:81], v[98:99] op_sel_hi:[1,0]
	v_cvt_pk_bf16_f32 v80, v84, v85
; #define GAS __attribute__((address_space(1)))
; __device__ __forceinline__ unsigned cvt_pk_bf16(float lo, float hi) { unsigned r; asm volatile("v_cvt_pk_bf16_f32 %0, %1, %2" : "=v"(r) : "v"(lo), "v"(hi)); return r; }
;     __device__ __forceinline__ void operator()(const f32x4 (&acc)[2][2][4][2], const Unit& u, int wr, int wc, int fr, int fq) const {
;         const int row0 = u.pm * BM + wr * 64 + fr, col0 = u.pn * BM + wc * 32 + 8 * fq;
; #pragma unroll
;         for (int ai = 0; ai < 2; ++ai)
; #pragma unroll
;             for (int m = 0; m < 4; ++m) { const int r = row0 + ai * HALF + m * 16; float s = rs ? *(const GAS float*)(rs + r) : 1.f; if (ssqp) s = rsqrtf((float)*(const GAS u64_t*)(ssqp + r) * (SSQ_INV / DM) + EPS); bf16_t* rowp = O + (size_t)r * ldc + col0;
; #pragma unroll
;                 for (int bj = 0; bj < 2; ++bj) { const f32x4 v0 = acc[ai][bj][m][0] * s, v1 = acc[ai][bj][m][1] * s;
;                     u32x4 w; w.x = cvt_pk_bf16(v0[0], v0[1]); w.y = cvt_pk_bf16(v0[2], v0[3]); w.z = cvt_pk_bf16(v1[0], v1[1]); w.w = cvt_pk_bf16(v1[2], v1[3]);
;                     *(GAS u32x4*)(rowp + bj * HALF) = w; } }
	v_cvt_pk_bf16_f32 v81, v86, v87
	s_nop 0
	v_cvt_pk_bf16_f32 v82, v82, v83
	v_cvt_pk_bf16_f32 v83, v88, v89
	global_store_dwordx4 v[96:97], v[80:83], off offset:256
	s_nop 3
	s_nop 1
	v_or_b32_e32 v80, 48, v138
	v_ashrrev_i32_e32 v81, 31, v80
	v_lshl_add_u64 v[82:83], v[80:81], 3, s[80:81]
	v_mov_b32_e32 v82, v160
	v_mov_b32_e32 v83, v161
	v_ffbh_u32_e32 v81, v83
	v_min_u32_e32 v81, 32, v81
	v_lshlrev_b64 v[82:83], v81, v[82:83]
	v_min_u32_e32 v82, 1, v82
	v_or_b32_e32 v82, v83, v82
	v_cvt_f32_u32_e32 v82, v82
	v_sub_u32_e32 v81, 32, v81
	v_ldexp_f32 v81, v82, v81
	v_fmamk_f32 v81, v81, 0x32000000, v232
	v_cmp_gt_f32_e32 vcc, s41, v81
	v_mul_f32_e32 v82, 0x4b800000, v81
	s_nop 0
	v_cndmask_b32_e32 v81, v81, v82, vcc
	v_rsq_f32_e32 v81, v81
	s_nop 0
	v_mul_f32_e32 v82, 0x45800000, v81
	v_cndmask_b32_e32 v82, v81, v82, vcc
	v_mad_i64_i32 v[80:81], s[38:39], v80, s40, v[142:143]
	v_lshl_add_u64 v[80:81], v[80:81], 0, v[144:145]
	v_pk_mul_f32 v[78:79], v[78:79], v[82:83] op_sel_hi:[1,0]
	v_pk_mul_f32 v[76:77], v[76:77], v[82:83] op_sel_hi:[1,0]
	v_pk_mul_f32 v[84:85], v[74:75], v[82:83] op_sel_hi:[1,0]
	v_pk_mul_f32 v[74:75], v[72:73], v[82:83] op_sel_hi:[1,0]
	v_cvt_pk_bf16_f32 v72, v76, v77
	v_cvt_pk_bf16_f32 v73, v78, v79
	v_pk_mul_f32 v[70:71], v[70:71], v[82:83] op_sel_hi:[1,0]
	v_cvt_pk_bf16_f32 v74, v74, v75
	v_cvt_pk_bf16_f32 v75, v84, v85
	global_store_dwordx4 v[80:81], v[72:75], off
	s_nop 3
	v_pk_mul_f32 v[68:69], v[68:69], v[82:83] op_sel_hi:[1,0]
	s_nop 0
	v_pk_mul_f32 v[72:73], v[66:67], v[82:83] op_sel_hi:[1,0]
	v_pk_mul_f32 v[66:67], v[64:65], v[82:83] op_sel_hi:[1,0]
	v_cvt_pk_bf16_f32 v64, v68, v69
	v_cvt_pk_bf16_f32 v65, v70, v71
	s_nop 0
	v_cvt_pk_bf16_f32 v66, v66, v67
	v_cvt_pk_bf16_f32 v67, v72, v73
	global_store_dwordx4 v[80:81], v[64:67], off offset:256
	s_nop 3
	s_nop 1
	v_mov_b32_e32 v64, v162
	v_mov_b32_e32 v65, v163
	s_nop 0
	v_add_u32_e32 v66, 0x80, v138
	v_ffbh_u32_e32 v67, v65
	v_min_u32_e32 v67, 32, v67
	v_lshlrev_b64 v[64:65], v67, v[64:65]
	v_min_u32_e32 v64, 1, v64
	v_or_b32_e32 v64, v65, v64
	v_cvt_f32_u32_e32 v64, v64
	v_sub_u32_e32 v65, 32, v67
	v_mad_i64_i32 v[66:67], s[38:39], v66, s40, v[142:143]
	v_ldexp_f32 v64, v64, v65
	v_fmamk_f32 v64, v64, 0x32000000, v232
	v_cmp_gt_f32_e32 vcc, s41, v64
	v_mul_f32_e32 v65, 0x4b800000, v64
	v_lshl_add_u64 v[66:67], v[66:67], 0, v[144:145]
	v_cndmask_b32_e32 v64, v64, v65, vcc
	v_rsq_f32_e32 v64, v64
	s_nop 0
	v_mul_f32_e32 v65, 0x45800000, v64
	v_cndmask_b32_e32 v64, v64, v65, vcc
	v_pk_mul_f32 v[62:63], v[62:63], v[64:65] op_sel_hi:[1,0]
	v_pk_mul_f32 v[60:61], v[60:61], v[64:65] op_sel_hi:[1,0]
	v_pk_mul_f32 v[68:69], v[58:59], v[64:65] op_sel_hi:[1,0]
	v_pk_mul_f32 v[58:59], v[56:57], v[64:65] op_sel_hi:[1,0]
	v_cvt_pk_bf16_f32 v56, v60, v61
	v_cvt_pk_bf16_f32 v57, v62, v63
	v_pk_mul_f32 v[54:55], v[54:55], v[64:65] op_sel_hi:[1,0]
	v_cvt_pk_bf16_f32 v58, v58, v59
	v_cvt_pk_bf16_f32 v59, v68, v69
	global_store_dwordx4 v[66:67], v[56:59], off
	s_nop 3
	v_pk_mul_f32 v[52:53], v[52:53], v[64:65] op_sel_hi:[1,0]
	s_nop 0
	v_pk_mul_f32 v[56:57], v[50:51], v[64:65] op_sel_hi:[1,0]
	v_pk_mul_f32 v[50:51], v[48:49], v[64:65] op_sel_hi:[1,0]
	v_cvt_pk_bf16_f32 v48, v52, v53
	v_cvt_pk_bf16_f32 v49, v54, v55
	s_nop 0
	v_cvt_pk_bf16_f32 v50, v50, v51
	v_cvt_pk_bf16_f32 v51, v56, v57
	global_store_dwordx4 v[66:67], v[48:51], off offset:256
	s_nop 3
	s_nop 1
	v_mov_b32_e32 v48, v164
	v_mov_b32_e32 v49, v165
	s_nop 0
	v_add_u32_e32 v50, 0x90, v138
	v_ffbh_u32_e32 v51, v49
	v_min_u32_e32 v51, 32, v51
	v_lshlrev_b64 v[48:49], v51, v[48:49]
	v_min_u32_e32 v48, 1, v48
	v_or_b32_e32 v48, v49, v48
	v_cvt_f32_u32_e32 v48, v48
	v_sub_u32_e32 v49, 32, v51
	v_mad_i64_i32 v[50:51], s[38:39], v50, s40, v[142:143]
	v_ldexp_f32 v48, v48, v49
	v_fmamk_f32 v48, v48, 0x32000000, v232
	v_cmp_gt_f32_e32 vcc, s41, v48
	v_mul_f32_e32 v49, 0x4b800000, v48
	v_lshl_add_u64 v[50:51], v[50:51], 0, v[144:145]
	v_cndmask_b32_e32 v48, v48, v49, vcc
	v_rsq_f32_e32 v48, v48
	s_nop 0
	v_mul_f32_e32 v49, 0x45800000, v48
	v_cndmask_b32_e32 v48, v48, v49, vcc
	v_pk_mul_f32 v[46:47], v[46:47], v[48:49] op_sel_hi:[1,0]
; #define GAS __attribute__((address_space(1)))
; __device__ __forceinline__ unsigned cvt_pk_bf16(float lo, float hi) { unsigned r; asm volatile("v_cvt_pk_bf16_f32 %0, %1, %2" : "=v"(r) : "v"(lo), "v"(hi)); return r; }
;     __device__ __forceinline__ void operator()(const f32x4 (&acc)[2][2][4][2], const Unit& u, int wr, int wc, int fr, int fq) const {
;         const int row0 = u.pm * BM + wr * 64 + fr, col0 = u.pn * BM + wc * 32 + 8 * fq;
; #pragma unroll
;         for (int ai = 0; ai < 2; ++ai)
; #pragma unroll
;             for (int m = 0; m < 4; ++m) { const int r = row0 + ai * HALF + m * 16; float s = rs ? *(const GAS float*)(rs + r) : 1.f; if (ssqp) s = rsqrtf((float)*(const GAS u64_t*)(ssqp + r) * (SSQ_INV / DM) + EPS); bf16_t* rowp = O + (size_t)r * ldc + col0;
; #pragma unroll
;                 for (int bj = 0; bj < 2; ++bj) { const f32x4 v0 = acc[ai][bj][m][0] * s, v1 = acc[ai][bj][m][1] * s;
;                     u32x4 w; w.x = cvt_pk_bf16(v0[0], v0[1]); w.y = cvt_pk_bf16(v0[2], v0[3]); w.z = cvt_pk_bf16(v1[0], v1[1]); w.w = cvt_pk_bf16(v1[2], v1[3]);
;                     *(GAS u32x4*)(rowp + bj * HALF) = w; } }
	v_pk_mul_f32 v[44:45], v[44:45], v[48:49] op_sel_hi:[1,0]
	v_pk_mul_f32 v[52:53], v[42:43], v[48:49] op_sel_hi:[1,0]
	v_pk_mul_f32 v[42:43], v[40:41], v[48:49] op_sel_hi:[1,0]
	v_cvt_pk_bf16_f32 v40, v44, v45
	v_cvt_pk_bf16_f32 v41, v46, v47
	v_pk_mul_f32 v[38:39], v[38:39], v[48:49] op_sel_hi:[1,0]
	v_cvt_pk_bf16_f32 v42, v42, v43
	v_cvt_pk_bf16_f32 v43, v52, v53
	global_store_dwordx4 v[50:51], v[40:43], off
	s_nop 3
	v_pk_mul_f32 v[36:37], v[36:37], v[48:49] op_sel_hi:[1,0]
	s_nop 0
	v_pk_mul_f32 v[40:41], v[34:35], v[48:49] op_sel_hi:[1,0]
	v_pk_mul_f32 v[34:35], v[32:33], v[48:49] op_sel_hi:[1,0]
	v_cvt_pk_bf16_f32 v32, v36, v37
	v_cvt_pk_bf16_f32 v33, v38, v39
	s_nop 0
	v_cvt_pk_bf16_f32 v34, v34, v35
	v_cvt_pk_bf16_f32 v35, v40, v41
	global_store_dwordx4 v[50:51], v[32:35], off offset:256
	s_nop 3
	s_nop 1
	v_mov_b32_e32 v32, v166
	v_mov_b32_e32 v33, v167
	s_nop 0
	v_add_u32_e32 v34, 0xa0, v138
	v_ffbh_u32_e32 v35, v33
	v_min_u32_e32 v35, 32, v35
	v_lshlrev_b64 v[32:33], v35, v[32:33]
	v_min_u32_e32 v32, 1, v32
	v_or_b32_e32 v32, v33, v32
	v_cvt_f32_u32_e32 v32, v32
	v_sub_u32_e32 v33, 32, v35
	v_mad_i64_i32 v[34:35], s[38:39], v34, s40, v[142:143]
	v_ldexp_f32 v32, v32, v33
	v_fmamk_f32 v32, v32, 0x32000000, v232
	v_cmp_gt_f32_e32 vcc, s41, v32
	v_mul_f32_e32 v33, 0x4b800000, v32
	v_lshl_add_u64 v[34:35], v[34:35], 0, v[144:145]
	v_cndmask_b32_e32 v32, v32, v33, vcc
	v_rsq_f32_e32 v32, v32
	s_nop 0
	v_mul_f32_e32 v33, 0x45800000, v32
	v_cndmask_b32_e32 v32, v32, v33, vcc
	v_pk_mul_f32 v[30:31], v[30:31], v[32:33] op_sel_hi:[1,0]
	v_pk_mul_f32 v[28:29], v[28:29], v[32:33] op_sel_hi:[1,0]
	v_pk_mul_f32 v[36:37], v[26:27], v[32:33] op_sel_hi:[1,0]
	v_pk_mul_f32 v[26:27], v[24:25], v[32:33] op_sel_hi:[1,0]
	v_cvt_pk_bf16_f32 v24, v28, v29
	v_cvt_pk_bf16_f32 v25, v30, v31
	v_pk_mul_f32 v[22:23], v[22:23], v[32:33] op_sel_hi:[1,0]
	v_cvt_pk_bf16_f32 v26, v26, v27
	v_cvt_pk_bf16_f32 v27, v36, v37
	global_store_dwordx4 v[34:35], v[24:27], off
	s_nop 3
	v_pk_mul_f32 v[20:21], v[20:21], v[32:33] op_sel_hi:[1,0]
	s_nop 0
	v_pk_mul_f32 v[24:25], v[18:19], v[32:33] op_sel_hi:[1,0]
	v_pk_mul_f32 v[18:19], v[16:17], v[32:33] op_sel_hi:[1,0]
	v_cvt_pk_bf16_f32 v16, v20, v21
	v_cvt_pk_bf16_f32 v17, v22, v23
	s_nop 0
	v_cvt_pk_bf16_f32 v18, v18, v19
	v_cvt_pk_bf16_f32 v19, v24, v25
	global_store_dwordx4 v[34:35], v[16:19], off offset:256
	s_nop 3
	s_nop 1
	v_mov_b32_e32 v16, v168
	v_mov_b32_e32 v17, v169
	s_nop 0
	v_add_u32_e32 v18, 0xb0, v138
	v_ffbh_u32_e32 v19, v17
	v_min_u32_e32 v19, 32, v19
	v_lshlrev_b64 v[16:17], v19, v[16:17]
	v_min_u32_e32 v16, 1, v16
	v_or_b32_e32 v16, v17, v16
	v_cvt_f32_u32_e32 v16, v16
	v_sub_u32_e32 v17, 32, v19
	v_mad_i64_i32 v[18:19], s[38:39], v18, s40, v[142:143]
	v_ldexp_f32 v16, v16, v17
	v_fmamk_f32 v16, v16, 0x32000000, v232
	v_cmp_gt_f32_e32 vcc, s41, v16
	v_mul_f32_e32 v17, 0x4b800000, v16
	v_lshl_add_u64 v[18:19], v[18:19], 0, v[144:145]
	v_cndmask_b32_e32 v16, v16, v17, vcc
	v_rsq_f32_e32 v16, v16
	s_mov_b64 s[38:39], -1
	v_mul_f32_e32 v17, 0x45800000, v16
	v_cndmask_b32_e32 v16, v16, v17, vcc
	v_pk_mul_f32 v[14:15], v[14:15], v[16:17] op_sel_hi:[1,0]
	v_pk_mul_f32 v[12:13], v[12:13], v[16:17] op_sel_hi:[1,0]
	v_pk_mul_f32 v[20:21], v[10:11], v[16:17] op_sel_hi:[1,0]
	v_pk_mul_f32 v[10:11], v[8:9], v[16:17] op_sel_hi:[1,0]
	v_cvt_pk_bf16_f32 v8, v12, v13
	v_cvt_pk_bf16_f32 v9, v14, v15
	v_pk_mul_f32 v[6:7], v[6:7], v[16:17] op_sel_hi:[1,0]
	v_cvt_pk_bf16_f32 v10, v10, v11
	v_cvt_pk_bf16_f32 v11, v20, v21
	global_store_dwordx4 v[18:19], v[8:11], off
	s_nop 3
	v_pk_mul_f32 v[4:5], v[4:5], v[16:17] op_sel_hi:[1,0]
	s_and_b64 vcc, exec, s[36:37]
	v_pk_mul_f32 v[8:9], v[2:3], v[16:17] op_sel_hi:[1,0]
	v_pk_mul_f32 v[2:3], v[0:1], v[16:17] op_sel_hi:[1,0]
	v_cvt_pk_bf16_f32 v0, v4, v5
	v_cvt_pk_bf16_f32 v1, v6, v7
	s_nop 0
	v_cvt_pk_bf16_f32 v2, v2, v3
	v_cvt_pk_bf16_f32 v3, v8, v9
	global_store_dwordx4 v[18:19], v[0:3], off offset:256
	s_nop 3
	s_cbranch_vccnz .LBB0_634
	s_andn2_b64 vcc, exec, s[14:15]
	v_mov_b32 v0, 0
	s_cbranch_vccnz .LBB0_633
	s_barrier
	s_branch .LBB0_633
